# norm row code: parameter loads hoisted/renamed to free registers with counted waits (no measurable change expected vs v3)
# baseline (speedup 1.0000x reference)
; __device__ __forceinline__ void p1_row(int row, const float* __restrict__ xsrc, const float* __restrict__ csrc, const float* __restrict__ modl, const float* __restrict__ nw,
;                                        bf16_t* __restrict__ H, int lane) {
;     ...
;     const f32x4* xr = (const f32x4*)(lat ? xsrc + (size_t)row * DM : csrc + (size_t)(row - MLAT) * DM) + lane;
;     f32x4 v[8]; float s = 0.f;
; #pragma unroll
;     for (int j = 0; j < 8; ++j) { v[j] = xr[64 * j]; s += (v[j][0] * v[j][0] + v[j][1] * v[j][1]) + (v[j][2] * v[j][2] + v[j][3] * v[j][3]); }
;     const float rinv = rsqrtf(wave_sum(s) * (1.f / DM) + EPS);
;     const f32x4* sh = (const f32x4*)(modl + mi * 6144) + lane; const f32x4* scl = (const f32x4*)(modl + mi * 6144 + DM) + lane; const f32x4* nwp = (const f32x4*)nw + lane;
;     u32x2* o8 = (u32x2*)(H + (size_t)row * DM) + lane;
; #pragma unroll
;     for (int j = 0; j < 8; ++j) { const f32x4 y = v[j] * rinv * nwp[64 * j] * (scl[64 * j] + 1.f) + sh[64 * j];
.LBB0_705:
	v_lshlrev_b32_e32 v176, 4, v64
	global_load_dwordx4 v[28:31], v176, s[28:29]
	global_load_dwordx4 v[24:27], v176, s[28:29] offset:1024
	v_lshl_add_u64 v[0:1], s[28:29], 0, v[176:177]
	global_load_dwordx4 v[20:23], v176, s[28:29] offset:2048
	global_load_dwordx4 v[16:19], v176, s[28:29] offset:3072
	s_movk_i32 s4, 0x1000
	v_add_co_u32_e32 v0, vcc, s4, v0
	s_mov_b32 s3, 0x800000
	s_nop 0
	v_addc_co_u32_e32 v1, vcc, 0, v1, vcc
	global_load_dwordx4 v[12:15], v[0:1], off
	s_min_i32 s2, s12, 0x4000
	s_ashr_i32 s2, s2, 12
	s_mulk_i32 s2, 0x1800
	s_waitcnt vmcnt(4)
	v_mov_b32_e32 v4, v29
	s_waitcnt vmcnt(3)
	v_mov_b32_e32 v5, v25
	v_mov_b32_e32 v2, v28
	v_mov_b32_e32 v3, v24
	v_pk_mul_f32 v[4:5], v[4:5], v[4:5]
	v_mov_b32_e32 v6, v31
	v_mov_b32_e32 v7, v27
	v_pk_fma_f32 v[2:3], v[2:3], v[2:3], v[4:5]
	v_mov_b32_e32 v4, v30
	v_mov_b32_e32 v5, v26
	v_pk_mul_f32 v[6:7], v[6:7], v[6:7]
	s_nop 0
	v_pk_fma_f32 v[4:5], v[4:5], v[4:5], v[6:7]
	s_waitcnt vmcnt(2)
	v_pk_mul_f32 v[6:7], v[20:21], v[20:21]
	v_pk_add_f32 v[2:3], v[2:3], v[4:5]
	v_pk_mul_f32 v[4:5], v[22:23], v[22:23]
	v_pk_add_f32 v[2:3], v[2:3], v[2:3] op_sel:[0,1] op_sel_hi:[1,0]
	v_pk_mov_b32 v[8:9], v[6:7], v[4:5] op_sel:[1,0]
	v_mov_b32_e32 v7, v5
	v_pk_add_f32 v[4:5], v[8:9], v[6:7]
	s_waitcnt vmcnt(0)
	v_mul_f32_e32 v6, v12, v12
	v_mul_f32_e32 v7, v13, v13
	v_pk_add_f32 v[4:5], v[4:5], v[4:5] op_sel:[0,1] op_sel_hi:[1,0]
	v_mov_b32_e32 v3, v6
	v_mov_b32_e32 v5, v7
	v_pk_add_f32 v[2:3], v[2:3], v[4:5]
	v_mul_f32_e32 v4, v17, v17
	v_mul_f32_e32 v6, v19, v19
	v_mul_f32_e32 v8, v14, v14
	v_mul_f32_e32 v9, v15, v15
	v_pk_fma_f32 v[4:5], v[16:17], v[16:17], v[4:5] op_sel_hi:[1,1,0]
	v_pk_fma_f32 v[6:7], v[18:19], v[18:19], v[6:7] op_sel_hi:[1,1,0]
	v_mov_b32_e32 v5, v8
	v_mov_b32_e32 v7, v9
	global_load_dwordx4 v[8:11], v[0:1], off offset:1024
	v_pk_add_f32 v[4:5], v[4:5], v[6:7]
	s_nop 0
	v_pk_add_f32 v[32:33], v[2:3], v[4:5]
	s_waitcnt vmcnt(0)
	v_pk_mul_f32 v[2:3], v[10:11], v[10:11]
	v_pk_mul_f32 v[4:5], v[8:9], v[8:9]
	v_pk_add_f32 v[32:33], v[32:33], v[32:33] op_sel:[0,1] op_sel_hi:[1,0]
	v_pk_mov_b32 v[6:7], v[4:5], v[2:3] op_sel:[1,0]
	v_mov_b32_e32 v5, v3
	v_pk_add_f32 v[34:35], v[6:7], v[4:5]
	global_load_dwordx4 v[4:7], v[0:1], off offset:2048
	s_nop 0
	global_load_dwordx4 v[0:3], v[0:1], off offset:3072
	v_pk_add_f32 v[34:35], v[34:35], v[34:35] op_sel:[0,1] op_sel_hi:[1,0]
	s_waitcnt vmcnt(0)
	v_mul_f32_e32 v36, v0, v0
	v_mul_f32_e32 v37, v1, v1
	v_mov_b32_e32 v33, v36
	v_mov_b32_e32 v35, v37
	v_pk_add_f32 v[32:33], v[32:33], v[34:35]
	v_mul_f32_e32 v34, v5, v5
	v_mul_f32_e32 v36, v7, v7
	v_mul_f32_e32 v38, v2, v2
	v_mul_f32_e32 v39, v3, v3
	v_pk_fma_f32 v[34:35], v[4:5], v[4:5], v[34:35] op_sel_hi:[1,1,0]
	v_pk_fma_f32 v[36:37], v[6:7], v[6:7], v[36:37] op_sel_hi:[1,1,0]
	v_mov_b32_e32 v35, v38
	v_mov_b32_e32 v37, v39
	v_pk_add_f32 v[34:35], v[34:35], v[36:37]
	s_nop 0
	v_pk_add_f32 v[32:33], v[32:33], v[34:35]
	v_xor_b32_e32 v34, 1, v228
	v_add_f32_e32 v32, v32, v33
	v_and_b32_e32 v33, 64, v228
	v_add_u32_e32 v33, 64, v33
	v_cmp_lt_i32_e32 vcc, v34, v33
	s_nop 1
	v_cndmask_b32_e32 v34, v228, v34, vcc
	v_lshlrev_b32_e32 v34, 2, v34
	ds_bpermute_b32 v34, v34, v32
	s_waitcnt lgkmcnt(0)
	v_add_f32_e32 v32, v32, v34
	v_xor_b32_e32 v34, 2, v228
	v_cmp_lt_i32_e32 vcc, v34, v33
	s_nop 1
	v_cndmask_b32_e32 v34, v228, v34, vcc
	v_lshlrev_b32_e32 v34, 2, v34
	ds_bpermute_b32 v34, v34, v32
	s_waitcnt lgkmcnt(0)
	v_add_f32_e32 v32, v32, v34
	v_xor_b32_e32 v34, 4, v228
	v_cmp_lt_i32_e32 vcc, v34, v33
	s_nop 1
	v_cndmask_b32_e32 v34, v228, v34, vcc
	v_lshlrev_b32_e32 v34, 2, v34
	ds_bpermute_b32 v34, v34, v32
	s_waitcnt lgkmcnt(0)
	v_add_f32_e32 v32, v32, v34
	v_xor_b32_e32 v34, 8, v228
	v_cmp_lt_i32_e32 vcc, v34, v33
	s_nop 1
	v_cndmask_b32_e32 v34, v228, v34, vcc
	v_lshlrev_b32_e32 v34, 2, v34
	ds_bpermute_b32 v34, v34, v32
	s_waitcnt lgkmcnt(0)
	v_add_f32_e32 v32, v32, v34
	v_xor_b32_e32 v34, 16, v228
	v_cmp_lt_i32_e32 vcc, v34, v33
	s_nop 1
	v_cndmask_b32_e32 v34, v228, v34, vcc
	v_lshlrev_b32_e32 v34, 2, v34
	ds_bpermute_b32 v34, v34, v32
	s_waitcnt lgkmcnt(0)
	v_add_f32_e32 v32, v32, v34
	v_xor_b32_e32 v34, 32, v228
	v_cmp_lt_i32_e32 vcc, v34, v33
	s_nop 1
	v_cndmask_b32_e32 v33, v228, v34, vcc
	v_lshlrev_b32_e32 v33, 2, v33
	ds_bpermute_b32 v33, v33, v32
	s_waitcnt lgkmcnt(0)
	s_waitcnt vmcnt(0)
	v_add_f32_e32 v32, v32, v33
	v_fmamk_f32 v32, v32, 0x3a000000, v178
	v_cmp_gt_f32_e32 vcc, s3, v32
	s_ashr_i32 s3, s2, 31
	s_lshl_b64 s[2:3], s[2:3], 2
	s_add_u32 s28, s56, s2
	s_addc_u32 s29, s57, s3
	global_load_dwordx4 v[112:115], v[66:67], off
	v_lshl_add_u64 v[38:39], s[28:29], 0, v[176:177]
	global_load_dwordx4 v[120:123], v176, s[28:29]
	global_load_dwordx4 v[124:127], v[66:67], off offset:1024
	global_load_dwordx4 v[132:135], v176, s[28:29] offset:1024
	global_load_dwordx4 v[136:139], v[66:67], off offset:2048
	global_load_dwordx4 v[144:147], v176, s[28:29] offset:2048
	global_load_dwordx4 v[152:155], v[66:67], off offset:3072
	global_load_dwordx4 v[160:163], v176, s[28:29] offset:3072
	global_load_dwordx4 v[164:167], v[70:71], off
	v_mul_f32_e32 v33, 0x4b800000, v32
	v_cndmask_b32_e32 v32, v32, v33, vcc
	v_rsq_f32_e32 v32, v32
	s_nop 0
	v_mul_f32_e32 v33, 0x45800000, v32
	v_cndmask_b32_e32 v32, v32, v33, vcc
	v_add_co_u32_e32 v168, vcc, s40, v38
	s_nop 1
	v_addc_co_u32_e32 v169, vcc, 0, v39, vcc
	global_load_dwordx4 v[116:119], v[168:169], off offset:-4096
	s_nop 0
	v_add_co_u32_e32 v170, vcc, s4, v38
	s_nop 1
	v_addc_co_u32_e32 v171, vcc, 0, v39, vcc
	v_pk_mul_f32 v[36:37], v[30:31], v[32:33] op_sel_hi:[1,0]
	v_pk_mul_f32 v[42:43], v[28:29], v[32:33] op_sel_hi:[1,0]
	s_lshl_b64 s[26:27], s[26:27], 12
	s_mov_b64 s[2:3], 0x2000
	v_lshl_add_u64 v[40:41], v[38:39], 0, s[2:3]
	global_load_dwordx4 v[128:131], v[40:41], off offset:1024
	global_load_dwordx4 v[140:143], v[40:41], off offset:2048
	global_load_dwordx4 v[156:159], v[40:41], off offset:3072
	v_lshl_add_u64 v[34:35], v[68:69], 0, s[26:27]
	s_waitcnt vmcnt(12)
; __device__ __forceinline__ unsigned cvt_pk_bf16(float lo, float hi) { unsigned r; asm volatile("v_cvt_pk_bf16_f32 %0, %1, %2" : "=v"(r) : "v"(lo), "v"(hi)); return r; }
; __device__ __forceinline__ void p1_row(int row, const float* __restrict__ xsrc, const float* __restrict__ csrc, const float* __restrict__ modl, const float* __restrict__ nw,
;                                        bf16_t* __restrict__ H, int lane) {
;     ...
;     for (int j = 0; j < 8; ++j) { const f32x4 y = v[j] * rinv * nwp[64 * j] * (scl[64 * j] + 1.f) + sh[64 * j];
;         u32x2 w; w.x = cvt_pk_bf16(y[0], y[1]); w.y = cvt_pk_bf16(y[2], y[3]); o8[64 * j] = w; }
	v_pk_mul_f32 v[44:45], v[114:115], v[36:37]
	v_pk_mul_f32 v[42:43], v[112:113], v[42:43]
	global_load_dwordx4 v[112:115], v[168:169], off
	s_waitcnt vmcnt(4)
	v_pk_add_f32 v[46:47], v[118:119], 1.0 op_sel_hi:[1,0]
	v_pk_add_f32 v[48:49], v[116:117], 1.0 op_sel_hi:[1,0]
	global_load_dwordx4 v[116:119], v[170:171], off
	v_pk_fma_f32 v[28:29], v[48:49], v[42:43], v[120:121]
	v_pk_fma_f32 v[30:31], v[46:47], v[44:45], v[122:123]
	global_load_dwordx4 v[120:123], v[72:73], off
	v_cvt_pk_bf16_f32 v28, v28, v29
	v_cvt_pk_bf16_f32 v29, v30, v31
	global_store_dwordx2 v[34:35], v[28:29], off
	v_pk_mul_f32 v[28:29], v[26:27], v[32:33] op_sel_hi:[1,0]
	v_pk_mul_f32 v[30:31], v[24:25], v[32:33] op_sel_hi:[1,0]
	v_pk_mul_f32 v[30:31], v[124:125], v[30:31]
	v_pk_mul_f32 v[28:29], v[126:127], v[28:29]
	global_load_dwordx4 v[124:127], v[168:169], off offset:1024
	s_waitcnt vmcnt(7)
	v_pk_add_f32 v[42:43], v[130:131], 1.0 op_sel_hi:[1,0]
	v_pk_add_f32 v[44:45], v[128:129], 1.0 op_sel_hi:[1,0]
	global_load_dwordx4 v[128:131], v[170:171], off offset:1024
	v_pk_fma_f32 v[24:25], v[44:45], v[30:31], v[132:133]
	v_pk_fma_f32 v[26:27], v[42:43], v[28:29], v[134:135]
	global_load_dwordx4 v[132:135], v[74:75], off
	v_cvt_pk_bf16_f32 v24, v24, v25
	v_cvt_pk_bf16_f32 v25, v26, v27
	global_store_dwordx2 v[34:35], v[24:25], off offset:512
	v_pk_mul_f32 v[24:25], v[22:23], v[32:33] op_sel_hi:[1,0]
	v_pk_mul_f32 v[26:27], v[20:21], v[32:33] op_sel_hi:[1,0]
	v_pk_mul_f32 v[26:27], v[26:27], v[136:137]
	v_pk_mul_f32 v[24:25], v[24:25], v[138:139]
	global_load_dwordx4 v[136:139], v[168:169], off offset:2048
	s_waitcnt vmcnt(10)
	v_pk_add_f32 v[28:29], v[142:143], 1.0 op_sel_hi:[1,0]
	v_pk_add_f32 v[30:31], v[140:141], 1.0 op_sel_hi:[1,0]
	global_load_dwordx4 v[140:143], v[170:171], off offset:2048
	v_pk_fma_f32 v[20:21], v[26:27], v[30:31], v[144:145]
	v_pk_fma_f32 v[22:23], v[24:25], v[28:29], v[146:147]
	global_load_dwordx4 v[144:147], v[76:77], off
	v_cvt_pk_bf16_f32 v20, v20, v21
	v_cvt_pk_bf16_f32 v21, v22, v23
	global_store_dwordx2 v[34:35], v[20:21], off offset:1024
	v_pk_mul_f32 v[20:21], v[18:19], v[32:33] op_sel_hi:[1,0]
	v_pk_mul_f32 v[22:23], v[16:17], v[32:33] op_sel_hi:[1,0]
	v_pk_mul_f32 v[22:23], v[22:23], v[152:153]
	v_pk_mul_f32 v[20:21], v[20:21], v[154:155]
	global_load_dwordx4 v[152:155], v[168:169], off offset:3072
	s_waitcnt vmcnt(13)
	v_pk_add_f32 v[24:25], v[158:159], 1.0 op_sel_hi:[1,0]
	v_pk_add_f32 v[26:27], v[156:157], 1.0 op_sel_hi:[1,0]
	global_load_dwordx4 v[156:159], v[170:171], off offset:3072
	v_pk_fma_f32 v[16:17], v[22:23], v[26:27], v[160:161]
	v_pk_fma_f32 v[18:19], v[20:21], v[24:25], v[162:163]
	v_cvt_pk_bf16_f32 v16, v16, v17
	v_cvt_pk_bf16_f32 v17, v18, v19
	global_store_dwordx2 v[34:35], v[16:17], off offset:1536
	v_pk_mul_f32 v[16:17], v[14:15], v[32:33] op_sel_hi:[1,0]
	v_pk_mul_f32 v[18:19], v[12:13], v[32:33] op_sel_hi:[1,0]
	v_pk_mul_f32 v[18:19], v[18:19], v[164:165]
	v_pk_mul_f32 v[20:21], v[16:17], v[166:167]
	s_waitcnt vmcnt(14)
	v_pk_add_f32 v[24:25], v[112:113], 1.0 op_sel_hi:[1,0]
	v_pk_add_f32 v[22:23], v[114:115], 1.0 op_sel_hi:[1,0]
	s_waitcnt vmcnt(13)
	v_pk_fma_f32 v[14:15], v[18:19], v[24:25], v[116:117]
	v_pk_fma_f32 v[16:17], v[20:21], v[22:23], v[118:119]
	v_cvt_pk_bf16_f32 v14, v14, v15
	v_cvt_pk_bf16_f32 v15, v16, v17
	global_store_dwordx2 v[34:35], v[14:15], off offset:2048
	v_pk_mul_f32 v[14:15], v[10:11], v[32:33] op_sel_hi:[1,0]
	v_pk_mul_f32 v[16:17], v[8:9], v[32:33] op_sel_hi:[1,0]
	s_waitcnt vmcnt(13)
	v_pk_mul_f32 v[16:17], v[16:17], v[120:121]
	v_pk_mul_f32 v[14:15], v[14:15], v[122:123]
	s_waitcnt vmcnt(11)
	v_pk_add_f32 v[18:19], v[126:127], 1.0 op_sel_hi:[1,0]
	v_pk_add_f32 v[20:21], v[124:125], 1.0 op_sel_hi:[1,0]
	s_waitcnt vmcnt(10)
	v_pk_fma_f32 v[8:9], v[16:17], v[20:21], v[128:129]
	v_pk_fma_f32 v[10:11], v[14:15], v[18:19], v[130:131]
	v_cvt_pk_bf16_f32 v8, v8, v9
	v_cvt_pk_bf16_f32 v9, v10, v11
	global_store_dwordx2 v[34:35], v[8:9], off offset:2560
	v_pk_mul_f32 v[8:9], v[6:7], v[32:33] op_sel_hi:[1,0]
	v_pk_mul_f32 v[10:11], v[4:5], v[32:33] op_sel_hi:[1,0]
	s_waitcnt vmcnt(10)
	v_pk_mul_f32 v[10:11], v[10:11], v[132:133]
	v_pk_mul_f32 v[8:9], v[8:9], v[134:135]
	s_waitcnt vmcnt(8)
	v_pk_add_f32 v[14:15], v[138:139], 1.0 op_sel_hi:[1,0]
	v_pk_add_f32 v[16:17], v[136:137], 1.0 op_sel_hi:[1,0]
	s_waitcnt vmcnt(7)
	v_pk_fma_f32 v[4:5], v[10:11], v[16:17], v[140:141]
	v_pk_fma_f32 v[6:7], v[8:9], v[14:15], v[142:143]
	v_cvt_pk_bf16_f32 v4, v4, v5
	v_cvt_pk_bf16_f32 v5, v6, v7
	global_store_dwordx2 v[34:35], v[4:5], off offset:3072
	v_pk_mul_f32 v[4:5], v[2:3], v[32:33] op_sel_hi:[1,0]
	v_pk_mul_f32 v[6:7], v[0:1], v[32:33] op_sel_hi:[1,0]
	s_waitcnt vmcnt(7)
	v_pk_mul_f32 v[6:7], v[6:7], v[144:145]
	v_pk_mul_f32 v[4:5], v[4:5], v[146:147]
	s_waitcnt vmcnt(5)
	v_pk_add_f32 v[8:9], v[154:155], 1.0 op_sel_hi:[1,0]
	v_pk_add_f32 v[10:11], v[152:153], 1.0 op_sel_hi:[1,0]
	s_waitcnt vmcnt(4)
	v_pk_fma_f32 v[0:1], v[6:7], v[10:11], v[156:157]
	v_pk_fma_f32 v[2:3], v[4:5], v[8:9], v[158:159]
	v_cvt_pk_bf16_f32 v0, v0, v1
	v_cvt_pk_bf16_f32 v1, v2, v3

; __device__ __forceinline__ void p1_row2(int rowA, int rowB, const float* __restrict__ xsrc, const float* __restrict__ csrc, const float* __restrict__ modl,
;                                         const float* __restrict__ nw, bf16_t* __restrict__ H, int lane) {
;     ...
;     const bool latA = rowA < MLAT, latB = rowB < MLAT; const int miA = latA ? (rowA >> 12) : 4, miB = latB ? (rowB >> 12) : 4;
;     const f32x4* xa = (const f32x4*)(latA ? xsrc + (size_t)rowA * DM : csrc + (size_t)(rowA - MLAT) * DM) + lane;
;     const f32x4* xb = (const f32x4*)(latB ? xsrc + (size_t)rowB * DM : csrc + (size_t)(rowB - MLAT) * DM) + lane;
;     f32x4 va[8], vb[8]; float sa = 0.f, sb = 0.f;
; #pragma unroll
;     for (int j = 0; j < 8; ++j) { va[j] = xa[64 * j]; vb[j] = xb[64 * j]; }
; #pragma unroll
;     for (int j = 0; j < 8; ++j) { sa += (va[j][0] * va[j][0] + va[j][1] * va[j][1]) + (va[j][2] * va[j][2] + va[j][3] * va[j][3]);
;                                   sb += (vb[j][0] * vb[j][0] + vb[j][1] * vb[j][1]) + (vb[j][2] * vb[j][2] + vb[j][3] * vb[j][3]); }
.LBB0_712:
	s_min_i32 s2, s12, 0x4000
	s_ashr_i32 s3, s2, 12
	s_min_u32 s2, s10, 0x4000
	s_lshr_b32 s2, s2, 12
	s_add_i32 s4, s12, 0xffffc000
	s_cmpk_lt_i32 s12, 0x4000
	v_readlane_b32 s28, v253, 57
	s_cselect_b32 s5, s13, 0
	s_cselect_b32 s4, s12, s4
	v_readlane_b32 s20, v251, 53
	v_readlane_b32 s30, v253, 59
	v_readlane_b32 s31, v253, 60
	v_readlane_b32 s28, v251, 52
	s_cselect_b32 s20, s31, s20
	s_cselect_b32 s28, s30, s28
	s_lshl_b64 s[4:5], s[4:5], 13
	v_readlane_b32 s29, v253, 58
	s_add_u32 s28, s28, s4
	s_addc_u32 s29, s20, s5
	v_lshlrev_b32_e32 v176, 4, v64
	s_nop 1
	global_load_dwordx4 v[60:63], v176, s[28:29]
	global_load_dwordx4 v[56:59], v176, s[26:27]
	global_load_dwordx4 v[52:55], v176, s[28:29] offset:1024
	global_load_dwordx4 v[48:51], v176, s[26:27] offset:1024
	global_load_dwordx4 v[40:43], v176, s[28:29] offset:2048
	global_load_dwordx4 v[44:47], v176, s[26:27] offset:2048
	global_load_dwordx4 v[36:39], v176, s[28:29] offset:3072
	global_load_dwordx4 v[32:35], v176, s[26:27] offset:3072
	v_lshl_add_u64 v[0:1], s[28:29], 0, v[176:177]
	s_movk_i32 s20, 0x1000
	v_add_co_u32_e32 v0, vcc, s20, v0
	v_lshl_add_u64 v[2:3], s[26:27], 0, v[176:177]
	s_nop 0
	v_addc_co_u32_e32 v1, vcc, 0, v1, vcc
	global_load_dwordx4 v[28:31], v[0:1], off
	v_add_co_u32_e32 v2, vcc, s20, v2
	s_mov_b32 s4, 0x3a000000
	s_nop 0
	v_addc_co_u32_e32 v3, vcc, 0, v3, vcc
	global_load_dwordx4 v[24:27], v[2:3], off
	global_load_dwordx4 v[20:23], v[0:1], off offset:1024
	global_load_dwordx4 v[16:19], v[2:3], off offset:1024
	global_load_dwordx4 v[12:15], v[0:1], off offset:2048
	global_load_dwordx4 v[8:11], v[2:3], off offset:2048
	global_load_dwordx4 v[4:7], v[0:1], off offset:3072
	s_nop 0
	global_load_dwordx4 v[0:3], v[2:3], off offset:3072
	s_mulk_i32 s2, 0x6000
	global_load_dwordx4 v[98:101], v[66:67], off
	s_waitcnt vmcnt(16)
	v_mov_b32_e32 v82, v61
	v_mov_b32_e32 v80, v60
	s_waitcnt vmcnt(14)
	v_mov_b32_e32 v83, v53
	v_mov_b32_e32 v81, v52
	v_pk_mul_f32 v[82:83], v[82:83], v[82:83]
	v_mov_b32_e32 v84, v63
	v_mov_b32_e32 v85, v55
	v_pk_fma_f32 v[80:81], v[80:81], v[80:81], v[82:83]
	v_mov_b32_e32 v82, v62
	v_mov_b32_e32 v83, v54
	v_pk_mul_f32 v[84:85], v[84:85], v[84:85]
	v_mov_b32_e32 v86, v59
	v_pk_fma_f32 v[82:83], v[82:83], v[82:83], v[84:85]
	v_mov_b32_e32 v84, v57
	s_waitcnt vmcnt(13)
	v_mov_b32_e32 v85, v49
	v_pk_add_f32 v[82:83], v[80:81], v[82:83]
	v_mov_b32_e32 v80, v56
	v_mov_b32_e32 v81, v48
	v_pk_mul_f32 v[84:85], v[84:85], v[84:85]
	v_mov_b32_e32 v87, v51
	v_pk_fma_f32 v[80:81], v[80:81], v[80:81], v[84:85]
	v_mov_b32_e32 v84, v58
	v_mov_b32_e32 v85, v50
	v_pk_mul_f32 v[86:87], v[86:87], v[86:87]
	s_waitcnt vmcnt(8)
	v_mul_f32_e32 v65, v28, v28
	v_pk_fma_f32 v[84:85], v[84:85], v[84:85], v[86:87]
	v_pk_mul_f32 v[86:87], v[40:41], v[40:41]
	v_pk_add_f32 v[80:81], v[80:81], v[84:85]
	v_pk_mul_f32 v[84:85], v[42:43], v[42:43]
	v_pk_add_f32 v[82:83], v[82:83], v[82:83] op_sel:[0,1] op_sel_hi:[1,0]
	v_pk_mov_b32 v[88:89], v[86:87], v[84:85] op_sel:[1,0]
	v_mov_b32_e32 v87, v85
	v_pk_add_f32 v[84:85], v[88:89], v[86:87]
	v_pk_mul_f32 v[86:87], v[46:47], v[46:47]
	v_pk_mul_f32 v[88:89], v[44:45], v[44:45]
	v_pk_add_f32 v[84:85], v[84:85], v[84:85] op_sel:[0,1] op_sel_hi:[1,0]
	v_pk_mov_b32 v[90:91], v[88:89], v[86:87] op_sel:[1,0]
	v_mov_b32_e32 v89, v87
	v_pk_add_f32 v[86:87], v[90:91], v[88:89]
	v_mul_f32_e32 v88, v29, v29
	v_mov_b32_e32 v83, v65
	v_mov_b32_e32 v85, v88
	v_pk_add_f32 v[82:83], v[82:83], v[84:85]
	v_mul_f32_e32 v84, v37, v37
	v_mul_f32_e32 v89, v30, v30
	v_pk_fma_f32 v[84:85], v[36:37], v[36:37], v[84:85] op_sel_hi:[1,1,0]
	v_mul_f32_e32 v88, v39, v39
	v_mul_f32_e32 v90, v31, v31
	v_mov_b32_e32 v85, v89
	v_pk_fma_f32 v[88:89], v[38:39], v[38:39], v[88:89] op_sel_hi:[1,1,0]
	s_waitcnt vmcnt(7)
	v_mul_f32_e32 v65, v24, v24
	v_mov_b32_e32 v89, v90
	v_pk_add_f32 v[84:85], v[84:85], v[88:89]
	v_mul_f32_e32 v88, v25, v25
	v_pk_add_f32 v[82:83], v[82:83], v[84:85]
	v_pk_add_f32 v[80:81], v[80:81], v[80:81] op_sel:[0,1] op_sel_hi:[1,0]
	v_pk_add_f32 v[84:85], v[86:87], v[86:87] op_sel:[0,1] op_sel_hi:[1,0]
	v_mov_b32_e32 v81, v65
	v_mov_b32_e32 v85, v88
	v_pk_add_f32 v[80:81], v[80:81], v[84:85]
	v_mul_f32_e32 v84, v33, v33
	v_mul_f32_e32 v86, v35, v35
	v_mul_f32_e32 v89, v26, v26
	v_mul_f32_e32 v90, v27, v27
	v_pk_fma_f32 v[84:85], v[32:33], v[32:33], v[84:85] op_sel_hi:[1,1,0]
	v_pk_fma_f32 v[86:87], v[34:35], v[34:35], v[86:87] op_sel_hi:[1,1,0]
	v_mov_b32_e32 v85, v89
	v_mov_b32_e32 v87, v90
	v_pk_add_f32 v[84:85], v[84:85], v[86:87]
	s_waitcnt vmcnt(6)
	v_pk_mul_f32 v[86:87], v[20:21], v[20:21]
	v_pk_add_f32 v[80:81], v[80:81], v[84:85]
	v_pk_mul_f32 v[84:85], v[22:23], v[22:23]
	s_waitcnt vmcnt(2)
	v_mul_f32_e32 v65, v4, v4
	v_pk_mov_b32 v[88:89], v[86:87], v[84:85] op_sel:[1,0]
	v_mov_b32_e32 v87, v85
	v_pk_add_f32 v[84:85], v[88:89], v[86:87]
	v_pk_mul_f32 v[86:87], v[18:19], v[18:19]
	v_pk_mul_f32 v[88:89], v[16:17], v[16:17]
	v_pk_add_f32 v[82:83], v[82:83], v[82:83] op_sel:[0,1] op_sel_hi:[1,0]
	v_pk_mov_b32 v[90:91], v[88:89], v[86:87] op_sel:[1,0]
	v_mov_b32_e32 v89, v87
	v_pk_add_f32 v[86:87], v[90:91], v[88:89]
	v_mul_f32_e32 v88, v5, v5
	v_pk_add_f32 v[84:85], v[84:85], v[84:85] op_sel:[0,1] op_sel_hi:[1,0]
	v_mov_b32_e32 v83, v65
	v_mov_b32_e32 v85, v88
	v_pk_add_f32 v[82:83], v[82:83], v[84:85]
	v_mul_f32_e32 v84, v13, v13
	v_mul_f32_e32 v89, v6, v6
	v_pk_fma_f32 v[84:85], v[12:13], v[12:13], v[84:85] op_sel_hi:[1,1,0]
	v_mul_f32_e32 v88, v15, v15
	v_mul_f32_e32 v90, v7, v7
	v_mov_b32_e32 v85, v89
	v_pk_fma_f32 v[88:89], v[14:15], v[14:15], v[88:89] op_sel_hi:[1,1,0]
	s_waitcnt vmcnt(1)
; __device__ __forceinline__ void p1_row2(int rowA, int rowB, const float* __restrict__ xsrc, const float* __restrict__ csrc, const float* __restrict__ modl,
;                                         const float* __restrict__ nw, bf16_t* __restrict__ H, int lane) {
;     ...
;     const float ra = rsqrtf(wave_sum(sa) * (1.f / DM) + EPS), rb = rsqrtf(wave_sum(sb) * (1.f / DM) + EPS);
;     const f32x4* nwp = (const f32x4*)nw + lane;
;     const f32x4* sha = (const f32x4*)(modl + miA * 6144) + lane; const f32x4* sca = (const f32x4*)(modl + miA * 6144 + DM) + lane;
;     const f32x4* shb = (const f32x4*)(modl + miB * 6144) + lane; const f32x4* scb = (const f32x4*)(modl + miB * 6144 + DM) + lane;
;     u32x2* oa = (u32x2*)(H + (size_t)rowA * DM) + lane; u32x2* ob = (u32x2*)(H + (size_t)rowB * DM) + lane;
	v_mul_f32_e32 v65, v0, v0
	v_mov_b32_e32 v89, v90
	v_pk_add_f32 v[84:85], v[84:85], v[88:89]
	v_mul_f32_e32 v88, v1, v1
	v_pk_add_f32 v[82:83], v[82:83], v[84:85]
	v_pk_add_f32 v[80:81], v[80:81], v[80:81] op_sel:[0,1] op_sel_hi:[1,0]
	v_pk_add_f32 v[84:85], v[86:87], v[86:87] op_sel:[0,1] op_sel_hi:[1,0]
	v_mov_b32_e32 v81, v65
	v_mov_b32_e32 v85, v88
	v_pk_add_f32 v[80:81], v[80:81], v[84:85]
	v_mul_f32_e32 v84, v9, v9
	v_mul_f32_e32 v86, v11, v11
	v_mul_f32_e32 v89, v2, v2
	v_mul_f32_e32 v90, v3, v3
	v_pk_fma_f32 v[84:85], v[8:9], v[8:9], v[84:85] op_sel_hi:[1,1,0]
	v_pk_fma_f32 v[86:87], v[10:11], v[10:11], v[86:87] op_sel_hi:[1,1,0]
	v_mov_b32_e32 v85, v89
	v_mov_b32_e32 v87, v90
	v_pk_add_f32 v[84:85], v[84:85], v[86:87]
	v_and_b32_e32 v65, 64, v228
	v_pk_add_f32 v[80:81], v[80:81], v[84:85]
	v_add_u32_e32 v65, 64, v65
	v_xor_b32_e32 v84, 1, v228
	v_cmp_lt_i32_e32 vcc, v84, v65
	v_mov_b32_e32 v85, v82
	v_mov_b32_e32 v82, v81
	v_cndmask_b32_e32 v84, v228, v84, vcc
	v_lshlrev_b32_e32 v86, 2, v84
	v_xor_b32_e32 v84, 2, v228
	v_cmp_lt_i32_e32 vcc, v84, v65
	s_nop 1
	v_cndmask_b32_e32 v84, v228, v84, vcc
	v_lshlrev_b32_e32 v87, 2, v84
	v_xor_b32_e32 v84, 4, v228
	v_cmp_lt_i32_e32 vcc, v84, v65
	s_nop 1
	v_cndmask_b32_e32 v84, v228, v84, vcc
	v_lshlrev_b32_e32 v88, 2, v84
	v_xor_b32_e32 v84, 8, v228
	v_cmp_lt_i32_e32 vcc, v84, v65
	s_nop 1
	v_cndmask_b32_e32 v84, v228, v84, vcc
	v_lshlrev_b32_e32 v89, 2, v84
	v_xor_b32_e32 v84, 16, v228
	v_cmp_lt_i32_e32 vcc, v84, v65
	s_nop 1
	v_cndmask_b32_e32 v84, v228, v84, vcc
	v_lshlrev_b32_e32 v90, 2, v84
	v_xor_b32_e32 v84, 32, v228
	v_cmp_lt_i32_e32 vcc, v84, v65
	s_nop 1
	v_cndmask_b32_e32 v65, v228, v84, vcc
	v_mov_b32_e32 v84, v80
	v_pk_add_f32 v[80:81], v[84:85], v[82:83]
	ds_bpermute_b32 v83, v86, v81
	ds_bpermute_b32 v82, v86, v80
	v_lshlrev_b32_e32 v65, 2, v65
	s_waitcnt lgkmcnt(0)
	v_pk_add_f32 v[80:81], v[80:81], v[82:83]
	ds_bpermute_b32 v83, v87, v81
	ds_bpermute_b32 v82, v87, v80
	s_waitcnt lgkmcnt(0)
	v_pk_add_f32 v[80:81], v[80:81], v[82:83]
	ds_bpermute_b32 v83, v88, v81
	ds_bpermute_b32 v82, v88, v80
	s_waitcnt lgkmcnt(0)
	v_pk_add_f32 v[80:81], v[80:81], v[82:83]
	ds_bpermute_b32 v83, v89, v81
	ds_bpermute_b32 v82, v89, v80
	s_waitcnt lgkmcnt(0)
	v_pk_add_f32 v[80:81], v[80:81], v[82:83]
	ds_bpermute_b32 v83, v90, v81
	ds_bpermute_b32 v82, v90, v80
	s_waitcnt lgkmcnt(0)
	v_pk_add_f32 v[80:81], v[80:81], v[82:83]
	ds_bpermute_b32 v83, v65, v81
	ds_bpermute_b32 v82, v65, v80
	s_waitcnt lgkmcnt(0)
	s_waitcnt vmcnt(0)
	v_pk_add_f32 v[80:81], v[80:81], v[82:83]
	v_pk_fma_f32 v[80:81], v[80:81], s[4:5], v[178:179] op_sel_hi:[1,0,0]
	s_mov_b32 s4, 0x800000
	v_cmp_gt_f32_e32 vcc, s4, v80
	global_load_dwordx4 v[128:131], v[66:67], off offset:1024
	global_load_dwordx4 v[152:155], v[66:67], off offset:2048
	v_mul_f32_e32 v65, 0x4b800000, v81
	v_cmp_gt_f32_e64 s[44:45], s4, v81
	s_mul_i32 s4, s3, 0x1800
	s_ashr_i32 s5, s4, 31
	s_lshl_b64 s[4:5], s[4:5], 2
	s_add_u32 s30, s56, s4
	s_addc_u32 s31, s57, s5
	v_lshl_add_u64 v[88:89], s[30:31], 0, v[176:177]
	global_load_dwordx4 v[112:115], v176, s[30:31]
	s_add_u32 s28, s56, s2
	s_addc_u32 s29, s57, 0
	v_lshl_add_u64 v[86:87], s[28:29], 0, v[176:177]
	global_load_dwordx4 v[124:127], v176, s[28:29]
	global_load_dwordx4 v[140:143], v176, s[30:31] offset:1024
	global_load_dwordx4 v[144:147], v176, s[28:29] offset:1024
	global_load_dwordx4 v[160:163], v176, s[30:31] offset:2048
	v_cndmask_b32_e64 v65, v81, v65, s[44:45]
	v_rsq_f32_e32 v65, v65
	s_nop 0
	v_mul_f32_e32 v81, 0x45800000, v65
	v_cndmask_b32_e64 v82, v65, v81, s[44:45]
	v_mul_f32_e32 v65, 0x4b800000, v80
	v_cndmask_b32_e32 v65, v80, v65, vcc
	v_rsq_f32_e32 v65, v65
	v_pk_mul_f32 v[60:61], v[60:61], v[82:83] op_sel_hi:[1,0]
	v_mul_f32_e32 v80, 0x45800000, v65
	v_cndmask_b32_e32 v80, v65, v80, vcc
	v_add_co_u32_e32 v168, vcc, s40, v88
	s_nop 1
	v_addc_co_u32_e32 v169, vcc, 0, v89, vcc
	global_load_dwordx4 v[116:119], v[168:169], off offset:-4096
	s_nop 0
	v_add_co_u32_e32 v170, vcc, s40, v86
	s_nop 1
	v_addc_co_u32_e32 v171, vcc, 0, v87, vcc
	global_load_dwordx4 v[120:123], v[170:171], off offset:-4096
	s_nop 0
	v_add_co_u32_e32 v172, vcc, s20, v88
	s_nop 1
	v_addc_co_u32_e32 v173, vcc, 0, v89, vcc
	s_nop 1
	v_add_co_u32_e32 v174, vcc, s20, v86
	s_nop 1
	v_addc_co_u32_e32 v175, vcc, 0, v87, vcc
	v_pk_mul_f32 v[106:107], v[98:99], v[60:61]
	v_pk_mul_f32 v[62:63], v[62:63], v[82:83] op_sel_hi:[1,0]
	v_pk_mul_f32 v[62:63], v[100:101], v[62:63]
	v_pk_mul_f32 v[58:59], v[58:59], v[80:81] op_sel_hi:[1,0]
	v_pk_mul_f32 v[56:57], v[56:57], v[80:81] op_sel_hi:[1,0]
	v_pk_mul_f32 v[100:101], v[100:101], v[58:59]
	v_pk_mul_f32 v[98:99], v[98:99], v[56:57]
	s_lshl_b64 s[26:27], s[10:11], 12
	s_mov_b64 s[4:5], 0x2000
	v_lshl_add_u64 v[92:93], v[88:89], 0, s[4:5]
	v_lshl_add_u64 v[90:91], v[86:87], 0, s[4:5]
	global_load_dwordx4 v[132:135], v[92:93], off offset:1024
	global_load_dwordx4 v[136:139], v[90:91], off offset:1024
	global_load_dwordx4 v[156:159], v[92:93], off offset:2048
	global_load_dwordx4 v[164:167], v[90:91], off offset:2048
	v_lshl_add_u64 v[84:85], v[68:69], 0, s[26:27]
	v_pk_mul_f32 v[54:55], v[54:55], v[82:83] op_sel_hi:[1,0]
	v_pk_mul_f32 v[52:53], v[52:53], v[82:83] op_sel_hi:[1,0]
	v_pk_mul_f32 v[50:51], v[50:51], v[80:81] op_sel_hi:[1,0]
	v_pk_mul_f32 v[48:49], v[48:49], v[80:81] op_sel_hi:[1,0]
	v_pk_mul_f32 v[42:43], v[42:43], v[82:83] op_sel_hi:[1,0]
	v_pk_mul_f32 v[40:41], v[40:41], v[82:83] op_sel_hi:[1,0]
	v_pk_mul_f32 v[38:39], v[38:39], v[82:83] op_sel_hi:[1,0]
	v_pk_mul_f32 v[36:37], v[36:37], v[82:83] op_sel_hi:[1,0]
	v_pk_mul_f32 v[34:35], v[34:35], v[80:81] op_sel_hi:[1,0]
	v_pk_mul_f32 v[32:33], v[32:33], v[80:81] op_sel_hi:[1,0]
	v_pk_mul_f32 v[30:31], v[30:31], v[82:83] op_sel_hi:[1,0]
	v_pk_mul_f32 v[28:29], v[28:29], v[82:83] op_sel_hi:[1,0]
	v_pk_mul_f32 v[26:27], v[26:27], v[80:81] op_sel_hi:[1,0]
	v_pk_mul_f32 v[24:25], v[24:25], v[80:81] op_sel_hi:[1,0]
	v_pk_mul_f32 v[22:23], v[22:23], v[82:83] op_sel_hi:[1,0]
	v_pk_mul_f32 v[20:21], v[20:21], v[82:83] op_sel_hi:[1,0]
	v_pk_mul_f32 v[18:19], v[18:19], v[80:81] op_sel_hi:[1,0]
	v_pk_mul_f32 v[16:17], v[16:17], v[80:81] op_sel_hi:[1,0]
	v_pk_mul_f32 v[14:15], v[14:15], v[82:83] op_sel_hi:[1,0]
	v_pk_mul_f32 v[12:13], v[12:13], v[82:83] op_sel_hi:[1,0]
	v_pk_mul_f32 v[10:11], v[10:11], v[80:81] op_sel_hi:[1,0]
	v_pk_mul_f32 v[8:9], v[8:9], v[80:81] op_sel_hi:[1,0]
	v_pk_mul_f32 v[6:7], v[6:7], v[82:83] op_sel_hi:[1,0]
	v_pk_mul_f32 v[4:5], v[4:5], v[82:83] op_sel_hi:[1,0]
	v_pk_mul_f32 v[2:3], v[2:3], v[80:81] op_sel_hi:[1,0]
	v_pk_mul_f32 v[0:1], v[0:1], v[80:81] op_sel_hi:[1,0]
	s_waitcnt vmcnt(5)
; __device__ __forceinline__ unsigned cvt_pk_bf16(float lo, float hi) { unsigned r; asm volatile("v_cvt_pk_bf16_f32 %0, %1, %2" : "=v"(r) : "v"(lo), "v"(hi)); return r; }
; __device__ __forceinline__ void p1_row2(int rowA, int rowB, const float* __restrict__ xsrc, const float* __restrict__ csrc, const float* __restrict__ modl,
;                                         const float* __restrict__ nw, bf16_t* __restrict__ H, int lane) {
;     ...
; #pragma unroll
;     for (int j = 0; j < 8; ++j) { const f32x4 w4 = nwp[64 * j];
;         const f32x4 ya = va[j] * ra * w4 * (sca[64 * j] + 1.f) + sha[64 * j], yb = vb[j] * rb * w4 * (scb[64 * j] + 1.f) + shb[64 * j];
;         u32x2 wa, wb; wa.x = cvt_pk_bf16(ya[0], ya[1]); wa.y = cvt_pk_bf16(ya[2], ya[3]); wb.x = cvt_pk_bf16(yb[0], yb[1]); wb.y = cvt_pk_bf16(yb[2], yb[3]);
;         oa[64 * j] = wa; ob[64 * j] = wb; }
	v_pk_add_f32 v[96:97], v[118:119], 1.0 op_sel_hi:[1,0]
	v_pk_add_f32 v[108:109], v[116:117], 1.0 op_sel_hi:[1,0]
	global_load_dwordx4 v[116:119], v[66:67], off offset:3072
	v_pk_fma_f32 v[94:95], v[96:97], v[62:63], v[114:115]
	v_pk_fma_f32 v[96:97], v[108:109], v[106:107], v[112:113]
	global_load_dwordx4 v[112:115], v176, s[28:29] offset:2048
	s_waitcnt vmcnt(6)
	v_pk_add_f32 v[102:103], v[122:123], 1.0 op_sel_hi:[1,0]
	v_pk_add_f32 v[104:105], v[120:121], 1.0 op_sel_hi:[1,0]
	global_load_dwordx4 v[120:123], v[92:93], off offset:3072
	v_cvt_pk_bf16_f32 v96, v96, v97
	v_cvt_pk_bf16_f32 v97, v94, v95
	v_pk_fma_f32 v[56:57], v[104:105], v[98:99], v[124:125]
	v_pk_fma_f32 v[58:59], v[102:103], v[100:101], v[126:127]
	global_load_dwordx4 v[124:127], v[90:91], off offset:3072
	v_cvt_pk_bf16_f32 v56, v56, v57
	v_cvt_pk_bf16_f32 v57, v58, v59
	global_store_dwordx2 v[78:79], v[96:97], off offset:-3584
	global_store_dwordx2 v[84:85], v[56:57], off
	v_pk_mul_f32 v[94:95], v[52:53], v[128:129]
	v_pk_mul_f32 v[96:97], v[54:55], v[130:131]
	v_pk_mul_f32 v[56:57], v[128:129], v[48:49]
	v_pk_mul_f32 v[58:59], v[130:131], v[50:51]
	global_load_dwordx4 v[128:131], v176, s[30:31] offset:3072
	s_waitcnt vmcnt(10)
	v_pk_add_f32 v[98:99], v[134:135], 1.0 op_sel_hi:[1,0]
	v_pk_add_f32 v[100:101], v[132:133], 1.0 op_sel_hi:[1,0]
	global_load_dwordx4 v[132:135], v176, s[28:29] offset:3072
	v_pk_fma_f32 v[54:55], v[96:97], v[98:99], v[142:143]
	v_pk_fma_f32 v[52:53], v[94:95], v[100:101], v[140:141]
	global_load_dwordx4 v[140:143], v[168:169], off
	s_waitcnt vmcnt(11)
	v_pk_add_f32 v[94:95], v[138:139], 1.0 op_sel_hi:[1,0]
	v_pk_add_f32 v[96:97], v[136:137], 1.0 op_sel_hi:[1,0]
	global_load_dwordx4 v[136:139], v[70:71], off
	v_cvt_pk_bf16_f32 v52, v52, v53
	v_cvt_pk_bf16_f32 v53, v54, v55
	v_pk_fma_f32 v[48:49], v[56:57], v[96:97], v[144:145]
	v_pk_fma_f32 v[50:51], v[58:59], v[94:95], v[146:147]
	global_load_dwordx4 v[144:147], v[172:173], off
	v_cvt_pk_bf16_f32 v48, v48, v49
	v_cvt_pk_bf16_f32 v49, v50, v51
	global_store_dwordx2 v[78:79], v[52:53], off offset:-3072
	global_store_dwordx2 v[84:85], v[48:49], off offset:512
	v_pk_mul_f32 v[52:53], v[40:41], v[152:153]
	v_pk_mul_f32 v[54:55], v[42:43], v[154:155]
	s_waitcnt vmcnt(14)
	v_pk_add_f32 v[56:57], v[158:159], 1.0 op_sel_hi:[1,0]
	v_pk_add_f32 v[58:59], v[156:157], 1.0 op_sel_hi:[1,0]
	global_load_dwordx4 v[156:159], v[174:175], off
	v_pk_fma_f32 v[54:55], v[54:55], v[56:57], v[162:163]
	v_pk_fma_f32 v[52:53], v[52:53], v[58:59], v[160:161]
	global_load_dwordx4 v[160:163], v[72:73], off
	v_pk_mul_f32 v[40:41], v[46:47], v[80:81] op_sel_hi:[1,0]
	v_pk_mul_f32 v[42:43], v[44:45], v[80:81] op_sel_hi:[1,0]
	v_pk_mul_f32 v[46:47], v[40:41], v[154:155]
	v_pk_mul_f32 v[44:45], v[42:43], v[152:153]
	global_load_dwordx4 v[152:155], v[170:171], off
	s_waitcnt vmcnt(16)
	v_pk_add_f32 v[48:49], v[166:167], 1.0 op_sel_hi:[1,0]
	v_pk_add_f32 v[50:51], v[164:165], 1.0 op_sel_hi:[1,0]
	global_load_dwordx4 v[164:167], v[168:169], off offset:1024
	s_waitcnt vmcnt(15)
	v_pk_fma_f32 v[40:41], v[44:45], v[50:51], v[112:113]
	v_cvt_pk_bf16_f32 v44, v52, v53
	v_cvt_pk_bf16_f32 v45, v54, v55
	v_pk_fma_f32 v[42:43], v[46:47], v[48:49], v[114:115]
	global_load_dwordx4 v[112:115], v[172:173], off offset:1024
	v_cvt_pk_bf16_f32 v40, v40, v41
	v_cvt_pk_bf16_f32 v41, v42, v43
	global_store_dwordx2 v[78:79], v[44:45], off offset:-2560
	global_store_dwordx2 v[84:85], v[40:41], off offset:1024
	v_pk_mul_f32 v[44:45], v[36:37], v[116:117]
	v_pk_mul_f32 v[46:47], v[38:39], v[118:119]
	v_pk_mul_f32 v[40:41], v[32:33], v[116:117]
	v_pk_mul_f32 v[42:43], v[34:35], v[118:119]
	global_load_dwordx4 v[116:119], v[170:171], off offset:1024
	s_waitcnt vmcnt(18)
	v_pk_add_f32 v[48:49], v[122:123], 1.0 op_sel_hi:[1,0]
	v_pk_add_f32 v[50:51], v[120:121], 1.0 op_sel_hi:[1,0]
	global_load_dwordx4 v[120:123], v[174:175], off offset:1024
	s_waitcnt vmcnt(15)
	v_pk_fma_f32 v[38:39], v[46:47], v[48:49], v[130:131]
	v_pk_fma_f32 v[36:37], v[44:45], v[50:51], v[128:129]
	global_load_dwordx4 v[128:131], v[168:169], off offset:2048
	v_pk_add_f32 v[44:45], v[126:127], 1.0 op_sel_hi:[1,0]
	v_pk_add_f32 v[46:47], v[124:125], 1.0 op_sel_hi:[1,0]
	global_load_dwordx4 v[124:127], v[74:75], off
	v_cvt_pk_bf16_f32 v36, v36, v37
	v_cvt_pk_bf16_f32 v37, v38, v39
	s_mov_b64 s[28:29], 0
	s_waitcnt vmcnt(16)
; __device__ __forceinline__ unsigned cvt_pk_bf16(float lo, float hi) { unsigned r; asm volatile("v_cvt_pk_bf16_f32 %0, %1, %2" : "=v"(r) : "v"(lo), "v"(hi)); return r; }
; __device__ __forceinline__ void p1_row2(int rowA, int rowB, const float* __restrict__ xsrc, const float* __restrict__ csrc, const float* __restrict__ modl,
;                                         const float* __restrict__ nw, bf16_t* __restrict__ H, int lane) {
;     ...
; #pragma unroll
;     for (int j = 0; j < 8; ++j) { const f32x4 w4 = nwp[64 * j];
;         const f32x4 ya = va[j] * ra * w4 * (sca[64 * j] + 1.f) + sha[64 * j], yb = vb[j] * rb * w4 * (scb[64 * j] + 1.f) + shb[64 * j];
;         u32x2 wa, wb; wa.x = cvt_pk_bf16(ya[0], ya[1]); wa.y = cvt_pk_bf16(ya[2], ya[3]); wb.x = cvt_pk_bf16(yb[0], yb[1]); wb.y = cvt_pk_bf16(yb[2], yb[3]);
;         oa[64 * j] = wa; ob[64 * j] = wb; }
	v_pk_fma_f32 v[32:33], v[40:41], v[46:47], v[132:133]
	v_pk_fma_f32 v[34:35], v[42:43], v[44:45], v[134:135]
	global_load_dwordx4 v[132:135], v[170:171], off offset:2048
	v_cvt_pk_bf16_f32 v32, v32, v33
	v_cvt_pk_bf16_f32 v33, v34, v35
	global_store_dwordx2 v[78:79], v[36:37], off offset:-2048
	global_store_dwordx2 v[84:85], v[32:33], off offset:1536
	s_waitcnt vmcnt(17)
	v_pk_mul_f32 v[40:41], v[28:29], v[136:137]
	v_pk_mul_f32 v[42:43], v[30:31], v[138:139]
	v_pk_mul_f32 v[34:35], v[26:27], v[138:139]
	v_pk_add_f32 v[44:45], v[140:141], 1.0 op_sel_hi:[1,0]
	v_pk_add_f32 v[30:31], v[142:143], 1.0 op_sel_hi:[1,0]
	global_load_dwordx4 v[140:143], v[174:175], off offset:2048
	s_waitcnt vmcnt(17)
	v_pk_fma_f32 v[36:37], v[40:41], v[44:45], v[144:145]
	v_pk_mul_f32 v[40:41], v[24:25], v[136:137]
	global_load_dwordx4 v[136:139], v[172:173], off offset:2048
	v_pk_fma_f32 v[38:39], v[42:43], v[30:31], v[146:147]
	global_load_dwordx4 v[144:147], v[76:77], off
	s_waitcnt vmcnt(14)
	v_pk_add_f32 v[42:43], v[152:153], 1.0 op_sel_hi:[1,0]
	v_pk_add_f32 v[26:27], v[154:155], 1.0 op_sel_hi:[1,0]
	global_load_dwordx4 v[152:155], v[168:169], off offset:3072
	v_pk_fma_f32 v[26:27], v[34:35], v[26:27], v[158:159]
	v_pk_fma_f32 v[30:31], v[40:41], v[42:43], v[156:157]
	global_load_dwordx4 v[156:159], v[170:171], off offset:3072
	v_cvt_pk_bf16_f32 v32, v36, v37
	v_cvt_pk_bf16_f32 v33, v38, v39
	v_cvt_pk_bf16_f32 v30, v30, v31
	v_cvt_pk_bf16_f32 v31, v26, v27
	global_store_dwordx2 v[78:79], v[32:33], off offset:-1536
	global_store_dwordx2 v[84:85], v[30:31], off offset:2048
	v_pk_mul_f32 v[26:27], v[20:21], v[160:161]
	v_pk_mul_f32 v[34:35], v[22:23], v[162:163]
	s_waitcnt vmcnt(17)
	v_pk_add_f32 v[36:37], v[166:167], 1.0 op_sel_hi:[1,0]
	v_pk_add_f32 v[38:39], v[164:165], 1.0 op_sel_hi:[1,0]
	global_load_dwordx4 v[164:167], v[174:175], off offset:3072
	s_waitcnt vmcnt(17)
	v_pk_fma_f32 v[20:21], v[26:27], v[38:39], v[112:113]
	v_pk_mul_f32 v[26:27], v[16:17], v[160:161]
	v_pk_mul_f32 v[30:31], v[18:19], v[162:163]
	global_load_dwordx4 v[160:163], v[172:173], off offset:3072
	v_pk_fma_f32 v[22:23], v[34:35], v[36:37], v[114:115]
	s_waitcnt vmcnt(15)
	v_pk_add_f32 v[32:33], v[118:119], 1.0 op_sel_hi:[1,0]
	v_pk_add_f32 v[34:35], v[116:117], 1.0 op_sel_hi:[1,0]
	v_cvt_pk_bf16_f32 v20, v20, v21
	v_cvt_pk_bf16_f32 v21, v22, v23
	s_waitcnt vmcnt(14)
	v_pk_fma_f32 v[16:17], v[26:27], v[34:35], v[120:121]
	v_pk_fma_f32 v[18:19], v[30:31], v[32:33], v[122:123]
	v_cvt_pk_bf16_f32 v16, v16, v17
	v_cvt_pk_bf16_f32 v17, v18, v19
	global_store_dwordx2 v[78:79], v[20:21], off offset:-1024
	global_store_dwordx2 v[84:85], v[16:17], off offset:2560
	s_waitcnt vmcnt(14)
	v_pk_mul_f32 v[20:21], v[12:13], v[124:125]
	v_pk_mul_f32 v[22:23], v[14:15], v[126:127]
	v_pk_mul_f32 v[16:17], v[8:9], v[124:125]
	v_pk_mul_f32 v[18:19], v[10:11], v[126:127]
	v_pk_add_f32 v[26:27], v[130:131], 1.0 op_sel_hi:[1,0]
	v_pk_add_f32 v[30:31], v[128:129], 1.0 op_sel_hi:[1,0]
	s_waitcnt vmcnt(9)
	v_pk_fma_f32 v[14:15], v[22:23], v[26:27], v[138:139]
	v_pk_fma_f32 v[12:13], v[20:21], v[30:31], v[136:137]
	v_pk_add_f32 v[20:21], v[134:135], 1.0 op_sel_hi:[1,0]
	v_pk_add_f32 v[22:23], v[132:133], 1.0 op_sel_hi:[1,0]
	v_cvt_pk_bf16_f32 v12, v12, v13
	v_cvt_pk_bf16_f32 v13, v14, v15
	v_pk_fma_f32 v[8:9], v[16:17], v[22:23], v[140:141]
	v_pk_fma_f32 v[10:11], v[18:19], v[20:21], v[142:143]
	v_cvt_pk_bf16_f32 v8, v8, v9
	v_cvt_pk_bf16_f32 v9, v10, v11
	global_store_dwordx2 v[78:79], v[12:13], off offset:-512
	global_store_dwordx2 v[84:85], v[8:9], off offset:3072
	s_waitcnt vmcnt(10)
	v_pk_mul_f32 v[12:13], v[4:5], v[144:145]
	v_pk_mul_f32 v[14:15], v[6:7], v[146:147]
	v_pk_mul_f32 v[8:9], v[0:1], v[144:145]
	v_pk_mul_f32 v[10:11], v[2:3], v[146:147]
	s_waitcnt vmcnt(9)
	v_pk_add_f32 v[16:17], v[154:155], 1.0 op_sel_hi:[1,0]
	v_pk_add_f32 v[18:19], v[152:153], 1.0 op_sel_hi:[1,0]
	s_waitcnt vmcnt(4)
	v_pk_fma_f32 v[6:7], v[14:15], v[16:17], v[162:163]
	v_pk_fma_f32 v[4:5], v[12:13], v[18:19], v[160:161]
	v_pk_add_f32 v[12:13], v[158:159], 1.0 op_sel_hi:[1,0]
	v_pk_add_f32 v[14:15], v[156:157], 1.0 op_sel_hi:[1,0]
	v_cvt_pk_bf16_f32 v4, v4, v5
	v_cvt_pk_bf16_f32 v5, v6, v7
	v_pk_fma_f32 v[0:1], v[8:9], v[14:15], v[164:165]
	v_pk_fma_f32 v[2:3], v[10:11], v[12:13], v[166:167]
	v_cvt_pk_bf16_f32 v0, v0, v1
	v_cvt_pk_bf16_f32 v1, v2, v3
	global_store_dwordx2 v[78:79], v[4:5], off

; __device__ __forceinline__ void p1_row(int row, const float* __restrict__ xsrc, const float* __restrict__ csrc, const float* __restrict__ modl, const float* __restrict__ nw,
;                                        bf16_t* __restrict__ H, int lane) {
;     ...
;     const f32x4* xr = (const f32x4*)(lat ? xsrc + (size_t)row * DM : csrc + (size_t)(row - MLAT) * DM) + lane;
;     f32x4 v[8]; float s = 0.f;
; #pragma unroll
;     for (int j = 0; j < 8; ++j) { v[j] = xr[64 * j]; s += (v[j][0] * v[j][0] + v[j][1] * v[j][1]) + (v[j][2] * v[j][2] + v[j][3] * v[j][3]); }
;     const float rinv = rsqrtf(wave_sum(s) * (1.f / DM) + EPS);
;     const f32x4* sh = (const f32x4*)(modl + mi * 6144) + lane; const f32x4* scl = (const f32x4*)(modl + mi * 6144 + DM) + lane; const f32x4* nwp = (const f32x4*)nw + lane;
.LBB0_720:
	v_lshlrev_b32_e32 v176, 4, v188
	global_load_dwordx4 v[28:31], v176, s[14:15]
	global_load_dwordx4 v[24:27], v176, s[14:15] offset:1024
	global_load_dwordx4 v[20:23], v176, s[14:15] offset:2048
	global_load_dwordx4 v[16:19], v176, s[14:15] offset:3072
	v_lshl_add_u64 v[0:1], s[14:15], 0, v[176:177]
	s_movk_i32 s10, 0x1000
	v_add_co_u32_e32 v4, vcc, s10, v0
	s_min_i32 s3, s12, 0x4000
	s_nop 0
	v_addc_co_u32_e32 v5, vcc, 0, v1, vcc
	global_load_dwordx4 v[12:15], v[4:5], off
	global_load_dwordx4 v[8:11], v[4:5], off offset:1024
	global_load_dwordx4 v[0:3], v[4:5], off offset:3072
	s_nop 0
	global_load_dwordx4 v[4:7], v[4:5], off offset:2048
	s_ashr_i32 s3, s3, 12
	s_mul_i32 s4, s3, 0x1800
	s_ashr_i32 s5, s4, 31
	v_and_b32_e32 v32, 64, v228
	s_lshl_b64 s[4:5], s[4:5], 2
	v_readlane_b32 s3, v254, 51
	v_xor_b32_e32 v33, 1, v228
	v_add_u32_e32 v78, 64, v32
	s_add_u32 s26, s3, s4
	v_readlane_b32 s3, v254, 52
	v_cmp_lt_i32_e32 vcc, v33, v78
	s_addc_u32 s27, s3, s5
	v_lshl_add_u64 v[34:35], s[26:27], 0, v[176:177]
	v_cndmask_b32_e32 v32, v228, v33, vcc
	v_lshlrev_b32_e32 v79, 2, v32
	v_add_co_u32_e32 v32, vcc, s40, v34
	global_load_dwordx4 v[38:41], v[64:65], off
	s_nop 0
	v_addc_co_u32_e32 v33, vcc, 0, v35, vcc
	global_load_dwordx4 v[42:45], v176, s[26:27]
	global_load_dwordx4 v[46:49], v[32:33], off offset:-4096
	s_mov_b32 s3, 0x800000
	s_mov_b64 s[4:5], 0x2000
	s_lshl_b64 s[14:15], s[12:13], 12
	s_waitcnt vmcnt(0)
	v_mov_b32_e32 v50, v29
	v_mov_b32_e32 v51, v25
	v_mov_b32_e32 v54, v31
	v_mov_b32_e32 v55, v27
	v_mov_b32_e32 v36, v28
	v_mov_b32_e32 v37, v24
	v_mov_b32_e32 v52, v30
	v_mov_b32_e32 v53, v26
	v_pk_mul_f32 v[56:57], v[22:23], v[22:23]
	v_pk_mul_f32 v[58:59], v[20:21], v[20:21]
	v_pk_mul_f32 v[50:51], v[50:51], v[50:51]
	v_pk_mul_f32 v[54:55], v[54:55], v[54:55]
	v_pk_mov_b32 v[76:77], v[58:59], v[56:57] op_sel:[1,0]
	v_mov_b32_e32 v59, v57
	v_pk_fma_f32 v[36:37], v[36:37], v[36:37], v[50:51]
	v_pk_fma_f32 v[50:51], v[52:53], v[52:53], v[54:55]
	v_mul_f32_e32 v60, v17, v17
	v_mul_f32_e32 v62, v19, v19
	v_pk_add_f32 v[52:53], v[76:77], v[58:59]
	v_pk_add_f32 v[36:37], v[36:37], v[50:51]
	v_pk_fma_f32 v[56:57], v[16:17], v[16:17], v[60:61] op_sel_hi:[1,1,0]
	v_pk_fma_f32 v[60:61], v[18:19], v[18:19], v[62:63] op_sel_hi:[1,1,0]
	v_mul_f32_e32 v77, v12, v12
	v_mul_f32_e32 v80, v13, v13
	v_pk_add_f32 v[50:51], v[52:53], v[52:53] op_sel:[0,1] op_sel_hi:[1,0]
	v_pk_add_f32 v[36:37], v[36:37], v[36:37] op_sel:[0,1] op_sel_hi:[1,0]
	v_mul_f32_e32 v57, v14, v14
	v_mul_f32_e32 v61, v15, v15
	v_pk_mul_f32 v[54:55], v[10:11], v[10:11]
	v_pk_mul_f32 v[58:59], v[8:9], v[8:9]
	v_mov_b32_e32 v51, v80
	v_mov_b32_e32 v37, v77
	v_pk_mov_b32 v[52:53], v[58:59], v[54:55] op_sel:[1,0]
	v_mov_b32_e32 v59, v55
	v_pk_add_f32 v[56:57], v[56:57], v[60:61]
	v_pk_add_f32 v[36:37], v[36:37], v[50:51]
	v_mul_f32_e32 v62, v5, v5
	v_mul_f32_e32 v76, v7, v7
	v_pk_add_f32 v[52:53], v[52:53], v[58:59]
	v_pk_add_f32 v[36:37], v[36:37], v[56:57]
	v_mul_f32_e32 v81, v0, v0
	v_mul_f32_e32 v82, v1, v1
	v_mul_f32_e32 v83, v2, v2
	v_mul_f32_e32 v84, v3, v3
	v_pk_fma_f32 v[54:55], v[4:5], v[4:5], v[62:63] op_sel_hi:[1,1,0]
	v_pk_fma_f32 v[62:63], v[6:7], v[6:7], v[76:77] op_sel_hi:[1,1,0]
	v_pk_add_f32 v[52:53], v[52:53], v[52:53] op_sel:[0,1] op_sel_hi:[1,0]
	v_pk_add_f32 v[36:37], v[36:37], v[36:37] op_sel:[0,1] op_sel_hi:[1,0]
	v_mov_b32_e32 v55, v83
	v_mov_b32_e32 v63, v84
	v_mov_b32_e32 v53, v82
	v_mov_b32_e32 v37, v81
	v_pk_add_f32 v[54:55], v[54:55], v[62:63]
	v_pk_add_f32 v[36:37], v[36:37], v[52:53]
	v_xor_b32_e32 v50, 2, v228
	v_pk_add_f32 v[36:37], v[36:37], v[54:55]
	v_cmp_lt_i32_e32 vcc, v50, v78
	v_add_f32_e32 v36, v36, v37
	ds_bpermute_b32 v37, v79, v36
	v_cndmask_b32_e32 v50, v228, v50, vcc
	v_lshlrev_b32_e32 v50, 2, v50
	v_pk_add_f32 v[48:49], v[48:49], 1.0 op_sel_hi:[1,0]
	v_pk_add_f32 v[46:47], v[46:47], 1.0 op_sel_hi:[1,0]
	s_waitcnt lgkmcnt(0)
	v_add_f32_e32 v36, v36, v37
	ds_bpermute_b32 v37, v50, v36
	v_xor_b32_e32 v50, 4, v228
	v_cmp_lt_i32_e32 vcc, v50, v78
	s_waitcnt lgkmcnt(0)
	v_add_f32_e32 v36, v36, v37
	v_cndmask_b32_e32 v50, v228, v50, vcc
	v_lshlrev_b32_e32 v50, 2, v50
	ds_bpermute_b32 v37, v50, v36
	v_xor_b32_e32 v50, 8, v228
	v_cmp_lt_i32_e32 vcc, v50, v78
	s_waitcnt lgkmcnt(0)
	v_add_f32_e32 v36, v36, v37
	v_cndmask_b32_e32 v50, v228, v50, vcc
	v_lshlrev_b32_e32 v50, 2, v50
	ds_bpermute_b32 v37, v50, v36
	v_xor_b32_e32 v50, 16, v228
	v_cmp_lt_i32_e32 vcc, v50, v78
	s_waitcnt lgkmcnt(0)
	v_add_f32_e32 v36, v36, v37
	v_cndmask_b32_e32 v50, v228, v50, vcc
	v_lshlrev_b32_e32 v50, 2, v50
	ds_bpermute_b32 v37, v50, v36
	v_xor_b32_e32 v50, 32, v228
	v_cmp_lt_i32_e32 vcc, v50, v78
	s_waitcnt lgkmcnt(0)
	v_add_f32_e32 v36, v36, v37
	v_cndmask_b32_e32 v50, v228, v50, vcc
	v_lshlrev_b32_e32 v50, 2, v50
	ds_bpermute_b32 v37, v50, v36
	v_lshl_add_u64 v[50:51], v[66:67], 0, s[14:15]
	s_waitcnt lgkmcnt(0)
	s_waitcnt vmcnt(0)
; __device__ __forceinline__ unsigned cvt_pk_bf16(float lo, float hi) { unsigned r; asm volatile("v_cvt_pk_bf16_f32 %0, %1, %2" : "=v"(r) : "v"(lo), "v"(hi)); return r; }
; __device__ __forceinline__ void p1_row(int row, const float* __restrict__ xsrc, const float* __restrict__ csrc, const float* __restrict__ modl, const float* __restrict__ nw,
;                                        bf16_t* __restrict__ H, int lane) {
;     ...
;     const float rinv = rsqrtf(wave_sum(s) * (1.f / DM) + EPS);
;     const f32x4* sh = (const f32x4*)(modl + mi * 6144) + lane; const f32x4* scl = (const f32x4*)(modl + mi * 6144 + DM) + lane; const f32x4* nwp = (const f32x4*)nw + lane;
;     u32x2* o8 = (u32x2*)(H + (size_t)row * DM) + lane;
; #pragma unroll
;     for (int j = 0; j < 8; ++j) { const f32x4 y = v[j] * rinv * nwp[64 * j] * (scl[64 * j] + 1.f) + sh[64 * j];
;         u32x2 w; w.x = cvt_pk_bf16(y[0], y[1]); w.y = cvt_pk_bf16(y[2], y[3]); o8[64 * j] = w; }
	v_add_f32_e32 v36, v36, v37
	v_fmamk_f32 v36, v36, 0x3a000000, v178
	v_cmp_gt_f32_e32 vcc, s3, v36
	global_load_dwordx4 v[112:115], v[64:65], off offset:1024
	global_load_dwordx4 v[120:123], v176, s[26:27] offset:1024
	global_load_dwordx4 v[124:127], v[64:65], off offset:2048
	global_load_dwordx4 v[132:135], v176, s[26:27] offset:2048
	global_load_dwordx4 v[136:139], v[64:65], off offset:3072
	global_load_dwordx4 v[144:147], v176, s[26:27] offset:3072
	global_load_dwordx4 v[152:155], v[68:69], off
	global_load_dwordx4 v[156:159], v[32:33], off
	global_load_dwordx4 v[164:167], v[70:71], off
	v_mul_f32_e32 v37, 0x4b800000, v36
	v_cndmask_b32_e32 v36, v36, v37, vcc
	v_rsq_f32_e32 v36, v36
	s_nop 0
	v_mul_f32_e32 v37, 0x45800000, v36
	v_cndmask_b32_e32 v36, v36, v37, vcc
	v_add_co_u32_e32 v168, vcc, s10, v34
	s_nop 1
	v_addc_co_u32_e32 v169, vcc, 0, v35, vcc
	global_load_dwordx4 v[160:163], v[168:169], off
	v_pk_mul_f32 v[30:31], v[30:31], v[36:37] op_sel_hi:[1,0]
	v_pk_mul_f32 v[28:29], v[28:29], v[36:37] op_sel_hi:[1,0]
	v_pk_mul_f32 v[30:31], v[40:41], v[30:31]
	v_pk_mul_f32 v[28:29], v[38:39], v[28:29]
	v_pk_fma_f32 v[30:31], v[48:49], v[30:31], v[44:45]
	v_lshl_add_u64 v[48:49], v[34:35], 0, s[4:5]
	global_load_dwordx4 v[116:119], v[48:49], off offset:1024
	global_load_dwordx4 v[128:131], v[48:49], off offset:2048
	global_load_dwordx4 v[140:143], v[48:49], off offset:3072
	v_pk_fma_f32 v[28:29], v[46:47], v[28:29], v[42:43]
	v_cvt_pk_bf16_f32 v46, v28, v29
	v_cvt_pk_bf16_f32 v47, v30, v31
	v_pk_mul_f32 v[26:27], v[26:27], v[36:37] op_sel_hi:[1,0]
	v_pk_mul_f32 v[24:25], v[24:25], v[36:37] op_sel_hi:[1,0]
	global_store_dwordx2 v[50:51], v[46:47], off
	v_pk_mul_f32 v[22:23], v[22:23], v[36:37] op_sel_hi:[1,0]
	v_pk_mul_f32 v[20:21], v[20:21], v[36:37] op_sel_hi:[1,0]
	v_pk_mul_f32 v[18:19], v[18:19], v[36:37] op_sel_hi:[1,0]
	v_pk_mul_f32 v[16:17], v[16:17], v[36:37] op_sel_hi:[1,0]
	v_pk_mul_f32 v[14:15], v[14:15], v[36:37] op_sel_hi:[1,0]
	v_pk_mul_f32 v[12:13], v[12:13], v[36:37] op_sel_hi:[1,0]
	v_pk_mul_f32 v[10:11], v[10:11], v[36:37] op_sel_hi:[1,0]
	v_pk_mul_f32 v[8:9], v[8:9], v[36:37] op_sel_hi:[1,0]
	v_pk_mul_f32 v[6:7], v[6:7], v[36:37] op_sel_hi:[1,0]
	v_pk_mul_f32 v[4:5], v[4:5], v[36:37] op_sel_hi:[1,0]
	v_pk_mul_f32 v[2:3], v[2:3], v[36:37] op_sel_hi:[1,0]
	v_pk_mul_f32 v[0:1], v[0:1], v[36:37] op_sel_hi:[1,0]
	s_waitcnt vmcnt(13)
	v_pk_mul_f32 v[24:25], v[112:113], v[24:25]
	v_pk_mul_f32 v[26:27], v[114:115], v[26:27]
	global_load_dwordx4 v[112:115], v[32:33], off offset:1024
	s_waitcnt vmcnt(4)
	v_pk_add_f32 v[28:29], v[118:119], 1.0 op_sel_hi:[1,0]
	v_pk_add_f32 v[30:31], v[116:117], 1.0 op_sel_hi:[1,0]
	global_load_dwordx4 v[116:119], v[168:169], off offset:1024
	v_pk_fma_f32 v[26:27], v[28:29], v[26:27], v[122:123]
	v_pk_fma_f32 v[24:25], v[30:31], v[24:25], v[120:121]
	global_load_dwordx4 v[120:123], v[72:73], off
	v_cvt_pk_bf16_f32 v42, v24, v25
	v_cvt_pk_bf16_f32 v43, v26, v27
	v_pk_mul_f32 v[20:21], v[20:21], v[124:125]
	v_pk_mul_f32 v[22:23], v[22:23], v[126:127]
	global_load_dwordx4 v[124:127], v[32:33], off offset:2048
	s_waitcnt vmcnt(6)
	v_pk_add_f32 v[24:25], v[130:131], 1.0 op_sel_hi:[1,0]
	v_pk_add_f32 v[26:27], v[128:129], 1.0 op_sel_hi:[1,0]
	global_load_dwordx4 v[128:131], v[168:169], off offset:2048
	v_pk_fma_f32 v[22:23], v[22:23], v[24:25], v[134:135]
	v_pk_fma_f32 v[20:21], v[20:21], v[26:27], v[132:133]
	global_load_dwordx4 v[132:135], v[74:75], off
	global_store_dwordx2 v[50:51], v[42:43], off offset:512
	v_cvt_pk_bf16_f32 v38, v20, v21
	v_cvt_pk_bf16_f32 v39, v22, v23
	v_pk_mul_f32 v[16:17], v[16:17], v[136:137]
	v_pk_mul_f32 v[18:19], v[18:19], v[138:139]
	global_load_dwordx4 v[136:139], v[32:33], off offset:3072
	s_waitcnt vmcnt(9)
	v_pk_add_f32 v[20:21], v[142:143], 1.0 op_sel_hi:[1,0]
	v_pk_add_f32 v[22:23], v[140:141], 1.0 op_sel_hi:[1,0]
	global_load_dwordx4 v[140:143], v[168:169], off offset:3072
	v_pk_fma_f32 v[18:19], v[18:19], v[20:21], v[146:147]
	v_pk_fma_f32 v[16:17], v[16:17], v[22:23], v[144:145]
	global_store_dwordx2 v[50:51], v[38:39], off offset:1024
	v_cvt_pk_bf16_f32 v28, v16, v17
	v_cvt_pk_bf16_f32 v29, v18, v19
	v_pk_mul_f32 v[12:13], v[12:13], v[152:153]
	v_pk_mul_f32 v[14:15], v[14:15], v[154:155]
	v_pk_add_f32 v[16:17], v[158:159], 1.0 op_sel_hi:[1,0]
	v_pk_add_f32 v[18:19], v[156:157], 1.0 op_sel_hi:[1,0]
	v_pk_fma_f32 v[14:15], v[14:15], v[16:17], v[162:163]
	v_pk_fma_f32 v[12:13], v[12:13], v[18:19], v[160:161]
	global_store_dwordx2 v[50:51], v[28:29], off offset:1536
	v_cvt_pk_bf16_f32 v24, v12, v13
	v_cvt_pk_bf16_f32 v25, v14, v15
	v_pk_mul_f32 v[8:9], v[8:9], v[164:165]
	v_pk_mul_f32 v[10:11], v[10:11], v[166:167]
	s_waitcnt vmcnt(10)
	v_pk_add_f32 v[12:13], v[114:115], 1.0 op_sel_hi:[1,0]
	v_pk_add_f32 v[14:15], v[112:113], 1.0 op_sel_hi:[1,0]
	s_waitcnt vmcnt(9)
	v_pk_fma_f32 v[10:11], v[10:11], v[12:13], v[118:119]
	v_pk_fma_f32 v[8:9], v[8:9], v[14:15], v[116:117]
	global_store_dwordx2 v[50:51], v[24:25], off offset:2048
	v_cvt_pk_bf16_f32 v20, v8, v9
	v_cvt_pk_bf16_f32 v21, v10, v11
	s_waitcnt vmcnt(9)
	v_pk_mul_f32 v[4:5], v[4:5], v[120:121]
	v_pk_mul_f32 v[6:7], v[6:7], v[122:123]
	s_waitcnt vmcnt(8)
	v_pk_add_f32 v[8:9], v[126:127], 1.0 op_sel_hi:[1,0]
	v_pk_add_f32 v[10:11], v[124:125], 1.0 op_sel_hi:[1,0]
	s_waitcnt vmcnt(7)
	v_pk_fma_f32 v[6:7], v[6:7], v[8:9], v[130:131]
	v_pk_fma_f32 v[4:5], v[4:5], v[10:11], v[128:129]
	global_store_dwordx2 v[50:51], v[20:21], off offset:2560
	v_cvt_pk_bf16_f32 v16, v4, v5
	v_cvt_pk_bf16_f32 v17, v6, v7
	s_waitcnt vmcnt(7)
	v_pk_mul_f32 v[0:1], v[0:1], v[132:133]
	v_pk_mul_f32 v[2:3], v[2:3], v[134:135]
	s_waitcnt vmcnt(5)
	v_pk_add_f32 v[6:7], v[136:137], 1.0 op_sel_hi:[1,0]
	v_pk_add_f32 v[4:5], v[138:139], 1.0 op_sel_hi:[1,0]
	s_waitcnt vmcnt(4)
	v_pk_fma_f32 v[0:1], v[0:1], v[6:7], v[140:141]
	global_store_dwordx2 v[50:51], v[16:17], off offset:3072
	v_pk_fma_f32 v[2:3], v[2:3], v[4:5], v[142:143]
	v_cvt_pk_bf16_f32 v0, v0, v1
	v_cvt_pk_bf16_f32 v1, v2, v3

; __device__ __forceinline__ void p1_row2(int rowA, int rowB, const float* __restrict__ xsrc, const float* __restrict__ csrc, const float* __restrict__ modl,
;                                         const float* __restrict__ nw, bf16_t* __restrict__ H, int lane) {
;     ...
;     const bool latA = rowA < MLAT, latB = rowB < MLAT; const int miA = latA ? (rowA >> 12) : 4, miB = latB ? (rowB >> 12) : 4;
;     const f32x4* xa = (const f32x4*)(latA ? xsrc + (size_t)rowA * DM : csrc + (size_t)(rowA - MLAT) * DM) + lane;
;     const f32x4* xb = (const f32x4*)(latB ? xsrc + (size_t)rowB * DM : csrc + (size_t)(rowB - MLAT) * DM) + lane;
;     f32x4 va[8], vb[8]; float sa = 0.f, sb = 0.f;
; #pragma unroll
;     for (int j = 0; j < 8; ++j) { va[j] = xa[64 * j]; vb[j] = xb[64 * j]; }
; #pragma unroll
;     for (int j = 0; j < 8; ++j) { sa += (va[j][0] * va[j][0] + va[j][1] * va[j][1]) + (va[j][2] * va[j][2] + va[j][3] * va[j][3]);
;                                   sb += (vb[j][0] * vb[j][0] + vb[j][1] * vb[j][1]) + (vb[j][2] * vb[j][2] + vb[j][3] * vb[j][3]); }
.LBB0_727:
	s_min_i32 s3, s12, 0x4000
	s_ashr_i32 s4, s3, 12
	s_min_u32 s3, s10, 0x4000
	s_lshr_b32 s3, s3, 12
	s_add_i32 s5, s12, 0xffffc000
	s_ashr_i32 s13, s12, 31
	s_cmpk_lt_i32 s12, 0x4000
	v_lshlrev_b32_e32 v176, 4, v188
	s_cselect_b32 s20, s12, s5
	v_readlane_b32 s5, v254, 45
	v_readlane_b32 s26, v254, 47
	global_load_dwordx4 v[56:59], v176, s[14:15]
	global_load_dwordx4 v[48:51], v176, s[14:15] offset:1024
	s_cselect_b32 s21, s13, 0
	s_cselect_b32 s5, s5, s26
	global_load_dwordx4 v[40:43], v176, s[14:15] offset:2048
	v_readlane_b32 s26, v254, 46
	v_readlane_b32 s27, v254, 48
	s_cselect_b32 s26, s26, s27
	s_lshl_b64 s[20:21], s[20:21], 13
	v_lshl_add_u64 v[0:1], s[14:15], 0, v[176:177]
	s_movk_i32 s30, 0x1000
	s_add_u32 s20, s26, s20
	v_add_co_u32_e32 v0, vcc, s30, v0
	s_addc_u32 s21, s5, s21
	s_nop 0
	v_addc_co_u32_e32 v1, vcc, 0, v1, vcc
	global_load_dwordx4 v[24:27], v[0:1], off
	global_load_dwordx4 v[60:63], v176, s[20:21]
	global_load_dwordx4 v[52:55], v176, s[20:21] offset:1024
	global_load_dwordx4 v[44:47], v176, s[20:21] offset:2048
	global_load_dwordx4 v[32:35], v176, s[20:21] offset:3072
	v_lshl_add_u64 v[2:3], s[20:21], 0, v[176:177]
	v_add_co_u32_e32 v4, vcc, s30, v2
	s_mulk_i32 s4, 0x1800
	s_nop 0
	v_addc_co_u32_e32 v5, vcc, 0, v3, vcc
	global_load_dwordx4 v[28:31], v[4:5], off
	global_load_dwordx4 v[36:39], v176, s[14:15] offset:3072
	global_load_dwordx4 v[20:23], v[4:5], off offset:1024
	global_load_dwordx4 v[16:19], v[0:1], off offset:1024
	global_load_dwordx4 v[8:11], v[0:1], off offset:2048
	s_nop 0
	global_load_dwordx4 v[0:3], v[0:1], off offset:3072
	s_nop 0
	global_load_dwordx4 v[12:15], v[4:5], off offset:2048
	s_nop 0
	global_load_dwordx4 v[4:7], v[4:5], off offset:3072
	s_ashr_i32 s5, s4, 31
	s_lshl_b64 s[4:5], s[4:5], 2
	v_readlane_b32 s14, v254, 51
	s_add_u32 s26, s14, s4
	v_readlane_b32 s4, v254, 52
	s_addc_u32 s27, s4, s5
	s_mulk_i32 s3, 0x6000
	s_add_u32 s28, s14, s3
	s_addc_u32 s29, s4, 0
	v_and_b32_e32 v108, 64, v228
	v_add_u32_e32 v110, 64, v108
	v_xor_b32_e32 v108, 1, v228
	s_mov_b32 s4, 0x3a000000
	s_mov_b32 s3, 0x800000
	s_lshl_b64 s[14:15], s[10:11], 12
	global_load_dwordx4 v[104:107], v176, s[28:29]
	s_waitcnt vmcnt(0)
	v_mov_b32_e32 v78, v57
	v_mov_b32_e32 v79, v49
	v_mov_b32_e32 v82, v59
	v_mov_b32_e32 v83, v51
	v_pk_mul_f32 v[84:85], v[42:43], v[42:43]
	v_pk_mul_f32 v[86:87], v[40:41], v[40:41]
	v_mov_b32_e32 v76, v56
	v_mov_b32_e32 v77, v48
	v_mov_b32_e32 v80, v58
	v_mov_b32_e32 v81, v50
	v_pk_mul_f32 v[78:79], v[78:79], v[78:79]
	v_pk_mul_f32 v[82:83], v[82:83], v[82:83]
	v_pk_mov_b32 v[88:89], v[86:87], v[84:85] op_sel:[1,0]
	v_mov_b32_e32 v87, v85
	v_pk_fma_f32 v[76:77], v[76:77], v[76:77], v[78:79]
	v_pk_fma_f32 v[78:79], v[80:81], v[80:81], v[82:83]
	v_pk_add_f32 v[80:81], v[88:89], v[86:87]
	v_mov_b32_e32 v82, v61
	v_mov_b32_e32 v83, v53
	v_mov_b32_e32 v86, v63
	v_mov_b32_e32 v87, v55
	v_pk_add_f32 v[76:77], v[76:77], v[78:79]
	v_mov_b32_e32 v78, v60
	v_mov_b32_e32 v79, v52
	v_mov_b32_e32 v84, v62
	v_mov_b32_e32 v85, v54
	v_pk_mul_f32 v[88:89], v[46:47], v[46:47]
	v_pk_mul_f32 v[90:91], v[44:45], v[44:45]
	v_pk_mul_f32 v[82:83], v[82:83], v[82:83]
	v_pk_mul_f32 v[86:87], v[86:87], v[86:87]
	v_pk_mov_b32 v[96:97], v[90:91], v[88:89] op_sel:[1,0]
	v_mov_b32_e32 v91, v89
	v_pk_fma_f32 v[78:79], v[78:79], v[78:79], v[82:83]
	v_pk_fma_f32 v[82:83], v[84:85], v[84:85], v[86:87]
	v_pk_add_f32 v[84:85], v[96:97], v[90:91]
	v_pk_add_f32 v[78:79], v[78:79], v[82:83]
	v_mul_f32_e32 v86, v28, v28
	v_mul_f32_e32 v87, v29, v29
	v_pk_add_f32 v[82:83], v[84:85], v[84:85] op_sel:[0,1] op_sel_hi:[1,0]
	v_pk_add_f32 v[78:79], v[78:79], v[78:79] op_sel:[0,1] op_sel_hi:[1,0]
	v_mov_b32_e32 v83, v87
	v_mov_b32_e32 v79, v86
	v_mul_f32_e32 v95, v24, v24
	v_mul_f32_e32 v92, v33, v33
	v_mul_f32_e32 v94, v35, v35
	v_pk_add_f32 v[78:79], v[78:79], v[82:83]
	v_mul_f32_e32 v82, v25, v25
	v_pk_add_f32 v[76:77], v[76:77], v[76:77] op_sel:[0,1] op_sel_hi:[1,0]
	v_pk_add_f32 v[80:81], v[80:81], v[80:81] op_sel:[0,1] op_sel_hi:[1,0]
	v_pk_fma_f32 v[88:89], v[32:33], v[32:33], v[92:93] op_sel_hi:[1,1,0]
	v_pk_fma_f32 v[92:93], v[34:35], v[34:35], v[94:95] op_sel_hi:[1,1,0]
	v_mov_b32_e32 v77, v95
	v_mov_b32_e32 v81, v82
	v_mul_f32_e32 v89, v30, v30
	v_mul_f32_e32 v93, v31, v31
	v_pk_add_f32 v[76:77], v[76:77], v[80:81]
	v_mul_f32_e32 v80, v37, v37
	v_pk_add_f32 v[84:85], v[88:89], v[92:93]
	v_mul_f32_e32 v83, v26, v26
	v_pk_fma_f32 v[80:81], v[36:37], v[36:37], v[80:81] op_sel_hi:[1,1,0]
	v_mul_f32_e32 v82, v39, v39
	v_pk_add_f32 v[78:79], v[78:79], v[84:85]
	v_mul_f32_e32 v84, v27, v27
	v_mov_b32_e32 v81, v83
	v_pk_fma_f32 v[82:83], v[38:39], v[38:39], v[82:83] op_sel_hi:[1,1,0]
	v_pk_add_f32 v[78:79], v[78:79], v[78:79] op_sel:[0,1] op_sel_hi:[1,0]
	v_mov_b32_e32 v83, v84
	v_pk_add_f32 v[80:81], v[80:81], v[82:83]
	v_pk_mul_f32 v[82:83], v[20:21], v[20:21]
	v_pk_add_f32 v[76:77], v[76:77], v[80:81]
	v_pk_mul_f32 v[80:81], v[22:23], v[22:23]
	v_pk_add_f32 v[76:77], v[76:77], v[76:77] op_sel:[0,1] op_sel_hi:[1,0]
	v_pk_mov_b32 v[84:85], v[82:83], v[80:81] op_sel:[1,0]
	v_mov_b32_e32 v83, v81
	v_pk_add_f32 v[80:81], v[84:85], v[82:83]
	v_pk_mul_f32 v[82:83], v[18:19], v[18:19]
	v_pk_mul_f32 v[84:85], v[16:17], v[16:17]
	v_pk_add_f32 v[80:81], v[80:81], v[80:81] op_sel:[0,1] op_sel_hi:[1,0]
	v_pk_mov_b32 v[86:87], v[84:85], v[82:83] op_sel:[1,0]
	v_mov_b32_e32 v85, v83
	v_pk_add_f32 v[82:83], v[86:87], v[84:85]
	v_mul_f32_e32 v84, v4, v4
	v_mul_f32_e32 v85, v5, v5
	v_mov_b32_e32 v79, v84
	v_mov_b32_e32 v81, v85
	v_pk_add_f32 v[78:79], v[78:79], v[80:81]
	v_mul_f32_e32 v80, v13, v13
	v_mul_f32_e32 v84, v15, v15
; __device__ __forceinline__ void p1_row2(int rowA, int rowB, const float* __restrict__ xsrc, const float* __restrict__ csrc, const float* __restrict__ modl,
;                                         const float* __restrict__ nw, bf16_t* __restrict__ H, int lane) {
;     ...
;     for (int j = 0; j < 8; ++j) { sa += (va[j][0] * va[j][0] + va[j][1] * va[j][1]) + (va[j][2] * va[j][2] + va[j][3] * va[j][3]);
;                                   sb += (vb[j][0] * vb[j][0] + vb[j][1] * vb[j][1]) + (vb[j][2] * vb[j][2] + vb[j][3] * vb[j][3]); }
;     const float ra = rsqrtf(wave_sum(sa) * (1.f / DM) + EPS), rb = rsqrtf(wave_sum(sb) * (1.f / DM) + EPS);
;     const f32x4* nwp = (const f32x4*)nw + lane;
;     const f32x4* sha = (const f32x4*)(modl + miA * 6144) + lane; const f32x4* sca = (const f32x4*)(modl + miA * 6144 + DM) + lane;
;     const f32x4* shb = (const f32x4*)(modl + miB * 6144) + lane; const f32x4* scb = (const f32x4*)(modl + miB * 6144 + DM) + lane;
;     u32x2* oa = (u32x2*)(H + (size_t)rowA * DM) + lane; u32x2* ob = (u32x2*)(H + (size_t)rowB * DM) + lane;
; #pragma unroll
;     for (int j = 0; j < 8; ++j) { const f32x4 w4 = nwp[64 * j];
;         const f32x4 ya = va[j] * ra * w4 * (sca[64 * j] + 1.f) + sha[64 * j], yb = vb[j] * rb * w4 * (scb[64 * j] + 1.f) + shb[64 * j];
	v_mul_f32_e32 v86, v6, v6
	v_mul_f32_e32 v87, v7, v7
	v_pk_fma_f32 v[80:81], v[12:13], v[12:13], v[80:81] op_sel_hi:[1,1,0]
	v_pk_fma_f32 v[84:85], v[14:15], v[14:15], v[84:85] op_sel_hi:[1,1,0]
	v_mov_b32_e32 v81, v86
	v_mov_b32_e32 v85, v87
	v_pk_add_f32 v[80:81], v[80:81], v[84:85]
	v_mul_f32_e32 v84, v1, v1
	v_pk_add_f32 v[80:81], v[78:79], v[80:81]
	v_mul_f32_e32 v78, v0, v0
	v_mov_b32_e32 v77, v78
	v_pk_add_f32 v[78:79], v[82:83], v[82:83] op_sel:[0,1] op_sel_hi:[1,0]
	v_mul_f32_e32 v82, v11, v11
	v_mov_b32_e32 v79, v84
	v_pk_add_f32 v[76:77], v[76:77], v[78:79]
	v_mul_f32_e32 v78, v9, v9
	v_mul_f32_e32 v85, v2, v2
	v_mul_f32_e32 v86, v3, v3
	v_pk_fma_f32 v[78:79], v[8:9], v[8:9], v[78:79] op_sel_hi:[1,1,0]
	v_pk_fma_f32 v[82:83], v[10:11], v[10:11], v[82:83] op_sel_hi:[1,1,0]
	v_mov_b32_e32 v79, v85
	v_mov_b32_e32 v83, v86
	v_pk_add_f32 v[78:79], v[78:79], v[82:83]
	v_lshl_add_u64 v[84:85], s[26:27], 0, v[176:177]
	v_pk_add_f32 v[82:83], v[76:77], v[78:79]
	v_add_co_u32_e32 v76, vcc, s40, v84
	v_lshl_add_u64 v[86:87], s[28:29], 0, v[176:177]
	s_nop 0
	v_addc_co_u32_e32 v77, vcc, 0, v85, vcc
	v_add_co_u32_e32 v78, vcc, s40, v86
	global_load_dwordx4 v[88:91], v[64:65], off
	global_load_dwordx4 v[92:95], v[76:77], off offset:-4096
	v_addc_co_u32_e32 v79, vcc, 0, v87, vcc
	global_load_dwordx4 v[96:99], v176, s[26:27]
	global_load_dwordx4 v[100:103], v[78:79], off offset:-4096
	v_cmp_lt_i32_e32 vcc, v108, v110
	v_mov_b32_e32 v109, v80
	v_mov_b32_e32 v80, v83
	v_cndmask_b32_e32 v108, v228, v108, vcc
	v_lshlrev_b32_e32 v111, 2, v108
	v_mov_b32_e32 v108, v82
	v_pk_add_f32 v[80:81], v[108:109], v[80:81]
	ds_bpermute_b32 v83, v111, v81
	ds_bpermute_b32 v82, v111, v80
	v_xor_b32_e32 v108, 2, v228
	v_cmp_lt_i32_e32 vcc, v108, v110
	s_waitcnt lgkmcnt(0)
	v_pk_add_f32 v[80:81], v[80:81], v[82:83]
	v_cndmask_b32_e32 v108, v228, v108, vcc
	v_lshlrev_b32_e32 v108, 2, v108
	ds_bpermute_b32 v83, v108, v81
	ds_bpermute_b32 v82, v108, v80
	v_xor_b32_e32 v108, 4, v228
	v_cmp_lt_i32_e32 vcc, v108, v110
	s_waitcnt lgkmcnt(0)
	v_pk_add_f32 v[80:81], v[80:81], v[82:83]
	v_cndmask_b32_e32 v108, v228, v108, vcc
	v_lshlrev_b32_e32 v108, 2, v108
	ds_bpermute_b32 v83, v108, v81
	ds_bpermute_b32 v82, v108, v80
	v_xor_b32_e32 v108, 8, v228
	v_cmp_lt_i32_e32 vcc, v108, v110
	s_waitcnt lgkmcnt(0)
	v_pk_add_f32 v[80:81], v[80:81], v[82:83]
	v_cndmask_b32_e32 v108, v228, v108, vcc
	v_lshlrev_b32_e32 v108, 2, v108
	ds_bpermute_b32 v83, v108, v81
	ds_bpermute_b32 v82, v108, v80
	v_xor_b32_e32 v108, 16, v228
	v_cmp_lt_i32_e32 vcc, v108, v110
	s_waitcnt lgkmcnt(0)
	v_pk_add_f32 v[80:81], v[80:81], v[82:83]
	v_cndmask_b32_e32 v108, v228, v108, vcc
	v_lshlrev_b32_e32 v108, 2, v108
	ds_bpermute_b32 v83, v108, v81
	ds_bpermute_b32 v82, v108, v80
	v_xor_b32_e32 v108, 32, v228
	v_cmp_lt_i32_e32 vcc, v108, v110
	s_waitcnt lgkmcnt(0)
	v_pk_add_f32 v[80:81], v[80:81], v[82:83]
	v_cndmask_b32_e32 v108, v228, v108, vcc
	v_lshlrev_b32_e32 v108, 2, v108
	ds_bpermute_b32 v83, v108, v81
	ds_bpermute_b32 v82, v108, v80
	s_waitcnt lgkmcnt(0)
	s_waitcnt vmcnt(0)
	v_pk_add_f32 v[80:81], v[80:81], v[82:83]
	v_pk_fma_f32 v[80:81], v[80:81], s[4:5], v[178:179] op_sel_hi:[1,0,0]
	s_mov_b64 s[4:5], 0x2000
	v_cmp_gt_f32_e32 vcc, s3, v81
	v_lshl_add_u64 v[108:109], v[84:85], 0, s[4:5]
	v_lshl_add_u64 v[110:111], v[86:87], 0, s[4:5]
	global_load_dwordx4 v[112:115], v[64:65], off offset:1024
	global_load_dwordx4 v[116:119], v[108:109], off offset:1024
	global_load_dwordx4 v[120:123], v176, s[26:27] offset:1024
	global_load_dwordx4 v[124:127], v[110:111], off offset:1024
	global_load_dwordx4 v[128:131], v176, s[28:29] offset:1024
	global_load_dwordx4 v[132:135], v[64:65], off offset:2048
	global_load_dwordx4 v[136:139], v[108:109], off offset:2048
	global_load_dwordx4 v[140:143], v[110:111], off offset:2048
	global_load_dwordx4 v[144:147], v176, s[26:27] offset:2048
	global_load_dwordx4 v[152:155], v176, s[28:29] offset:2048
	global_load_dwordx4 v[156:159], v[64:65], off offset:3072
	global_load_dwordx4 v[160:163], v[108:109], off offset:3072
	global_load_dwordx4 v[164:167], v[110:111], off offset:3072
	v_mul_f32_e32 v82, 0x4b800000, v81
	v_cmp_gt_f32_e64 s[44:45], s3, v80
	v_cndmask_b32_e32 v81, v81, v82, vcc
	v_mul_f32_e32 v82, 0x4b800000, v80
	v_rsq_f32_e32 v81, v81
	v_cndmask_b32_e64 v80, v80, v82, s[44:45]
	v_rsq_f32_e32 v82, v80
	v_mul_f32_e32 v80, 0x45800000, v81
	v_cndmask_b32_e32 v80, v81, v80, vcc
	v_add_co_u32_e32 v168, vcc, s30, v84
	s_nop 1
	v_addc_co_u32_e32 v169, vcc, 0, v85, vcc
	s_nop 1
	v_add_co_u32_e32 v170, vcc, s30, v86
	s_nop 1
	v_addc_co_u32_e32 v171, vcc, 0, v87, vcc
	v_mul_f32_e32 v81, 0x45800000, v82
	v_cndmask_b32_e64 v82, v82, v81, s[44:45]
	v_pk_mul_f32 v[62:63], v[62:63], v[80:81] op_sel_hi:[1,0]
	v_pk_mul_f32 v[60:61], v[60:61], v[80:81] op_sel_hi:[1,0]
	v_pk_mul_f32 v[62:63], v[90:91], v[62:63]
	v_pk_mul_f32 v[60:61], v[88:89], v[60:61]
	v_pk_add_f32 v[94:95], v[94:95], 1.0 op_sel_hi:[1,0]
	v_pk_add_f32 v[92:93], v[92:93], 1.0 op_sel_hi:[1,0]
	v_pk_mul_f32 v[58:59], v[58:59], v[82:83] op_sel_hi:[1,0]
	v_pk_mul_f32 v[56:57], v[56:57], v[82:83] op_sel_hi:[1,0]
	v_pk_fma_f32 v[62:63], v[94:95], v[62:63], v[98:99]
	v_pk_fma_f32 v[60:61], v[92:93], v[60:61], v[96:97]
	v_pk_mul_f32 v[56:57], v[88:89], v[56:57]
	v_pk_mul_f32 v[58:59], v[90:91], v[58:59]
	v_pk_add_f32 v[88:89], v[102:103], 1.0 op_sel_hi:[1,0]
	v_pk_add_f32 v[90:91], v[100:101], 1.0 op_sel_hi:[1,0]
	v_pk_fma_f32 v[58:59], v[88:89], v[58:59], v[106:107]
	v_pk_fma_f32 v[56:57], v[90:91], v[56:57], v[104:105]
	v_cvt_pk_bf16_f32 v104, v60, v61
	v_cvt_pk_bf16_f32 v105, v62, v63
	v_pk_mul_f32 v[54:55], v[54:55], v[80:81] op_sel_hi:[1,0]
; __device__ __forceinline__ unsigned cvt_pk_bf16(float lo, float hi) { unsigned r; asm volatile("v_cvt_pk_bf16_f32 %0, %1, %2" : "=v"(r) : "v"(lo), "v"(hi)); return r; }
; __device__ __forceinline__ void p1_row2(int rowA, int rowB, const float* __restrict__ xsrc, const float* __restrict__ csrc, const float* __restrict__ modl,
;                                         const float* __restrict__ nw, bf16_t* __restrict__ H, int lane) {
;     ...
; #pragma unroll
;     for (int j = 0; j < 8; ++j) { const f32x4 w4 = nwp[64 * j];
;         const f32x4 ya = va[j] * ra * w4 * (sca[64 * j] + 1.f) + sha[64 * j], yb = vb[j] * rb * w4 * (scb[64 * j] + 1.f) + shb[64 * j];
;         u32x2 wa, wb; wa.x = cvt_pk_bf16(ya[0], ya[1]); wa.y = cvt_pk_bf16(ya[2], ya[3]); wb.x = cvt_pk_bf16(yb[0], yb[1]); wb.y = cvt_pk_bf16(yb[2], yb[3]);
;         oa[64 * j] = wa; ob[64 * j] = wb; }
	v_cvt_pk_bf16_f32 v106, v56, v57
	v_cvt_pk_bf16_f32 v107, v58, v59
	v_pk_mul_f32 v[52:53], v[52:53], v[80:81] op_sel_hi:[1,0]
	v_pk_mul_f32 v[50:51], v[50:51], v[82:83] op_sel_hi:[1,0]
	v_pk_mul_f32 v[48:49], v[48:49], v[82:83] op_sel_hi:[1,0]
	s_lshl_b64 s[4:5], s[12:13], 12
	v_lshl_add_u64 v[56:57], v[66:67], 0, s[4:5]
	v_lshl_add_u64 v[58:59], v[66:67], 0, s[14:15]
	global_store_dwordx2 v[56:57], v[104:105], off
	global_store_dwordx2 v[58:59], v[106:107], off
	v_pk_mul_f32 v[46:47], v[46:47], v[80:81] op_sel_hi:[1,0]
	v_pk_mul_f32 v[44:45], v[44:45], v[80:81] op_sel_hi:[1,0]
	v_pk_mul_f32 v[42:43], v[42:43], v[82:83] op_sel_hi:[1,0]
	v_pk_mul_f32 v[40:41], v[40:41], v[82:83] op_sel_hi:[1,0]
	v_pk_mul_f32 v[34:35], v[34:35], v[80:81] op_sel_hi:[1,0]
	v_pk_mul_f32 v[38:39], v[38:39], v[82:83] op_sel_hi:[1,0]
	v_pk_mul_f32 v[36:37], v[36:37], v[82:83] op_sel_hi:[1,0]
	v_pk_mul_f32 v[32:33], v[32:33], v[80:81] op_sel_hi:[1,0]
	v_pk_mul_f32 v[30:31], v[30:31], v[80:81] op_sel_hi:[1,0]
	v_pk_mul_f32 v[28:29], v[28:29], v[80:81] op_sel_hi:[1,0]
	v_pk_mul_f32 v[26:27], v[26:27], v[82:83] op_sel_hi:[1,0]
	v_pk_mul_f32 v[24:25], v[24:25], v[82:83] op_sel_hi:[1,0]
	v_pk_mul_f32 v[22:23], v[22:23], v[80:81] op_sel_hi:[1,0]
	v_pk_mul_f32 v[20:21], v[20:21], v[80:81] op_sel_hi:[1,0]
	v_pk_mul_f32 v[18:19], v[18:19], v[82:83] op_sel_hi:[1,0]
	v_pk_mul_f32 v[16:17], v[16:17], v[82:83] op_sel_hi:[1,0]
	v_pk_mul_f32 v[14:15], v[14:15], v[80:81] op_sel_hi:[1,0]
	v_pk_mul_f32 v[12:13], v[12:13], v[80:81] op_sel_hi:[1,0]
	v_pk_mul_f32 v[10:11], v[10:11], v[82:83] op_sel_hi:[1,0]
	v_pk_mul_f32 v[8:9], v[8:9], v[82:83] op_sel_hi:[1,0]
	v_pk_mul_f32 v[6:7], v[6:7], v[80:81] op_sel_hi:[1,0]
	v_pk_mul_f32 v[4:5], v[4:5], v[80:81] op_sel_hi:[1,0]
	v_pk_mul_f32 v[2:3], v[2:3], v[82:83] op_sel_hi:[1,0]
	v_pk_mul_f32 v[0:1], v[0:1], v[82:83] op_sel_hi:[1,0]
	s_waitcnt vmcnt(14)
	v_pk_mul_f32 v[52:53], v[52:53], v[112:113]
	v_pk_mul_f32 v[54:55], v[54:55], v[114:115]
	s_waitcnt vmcnt(13)
	v_pk_add_f32 v[90:91], v[118:119], 1.0 op_sel_hi:[1,0]
	v_pk_add_f32 v[88:89], v[116:117], 1.0 op_sel_hi:[1,0]
	global_load_dwordx4 v[116:119], v176, s[28:29] offset:3072
	v_pk_mul_f32 v[48:49], v[112:113], v[48:49]
	v_pk_mul_f32 v[50:51], v[114:115], v[50:51]
	global_load_dwordx4 v[112:115], v176, s[26:27] offset:3072
	s_waitcnt vmcnt(13)
	v_pk_add_f32 v[60:61], v[126:127], 1.0 op_sel_hi:[1,0]
	v_pk_add_f32 v[62:63], v[124:125], 1.0 op_sel_hi:[1,0]
	global_load_dwordx4 v[124:127], v[76:77], off
	v_pk_fma_f32 v[54:55], v[54:55], v[90:91], v[122:123]
	v_pk_fma_f32 v[52:53], v[52:53], v[88:89], v[120:121]
	global_load_dwordx4 v[120:123], v[68:69], off
	s_waitcnt vmcnt(14)
	v_pk_fma_f32 v[50:51], v[50:51], v[60:61], v[130:131]
	v_pk_fma_f32 v[48:49], v[48:49], v[62:63], v[128:129]
	global_load_dwordx4 v[128:131], v[168:169], off
	v_cvt_pk_bf16_f32 v96, v52, v53
	v_cvt_pk_bf16_f32 v97, v54, v55
	v_cvt_pk_bf16_f32 v98, v48, v49
	v_cvt_pk_bf16_f32 v99, v50, v51
	global_store_dwordx2 v[56:57], v[96:97], off offset:512
	global_store_dwordx2 v[58:59], v[98:99], off offset:512
	s_waitcnt vmcnt(16)
	v_pk_mul_f32 v[44:45], v[44:45], v[132:133]
	v_pk_mul_f32 v[46:47], v[46:47], v[134:135]
	s_waitcnt vmcnt(15)
	v_pk_add_f32 v[54:55], v[138:139], 1.0 op_sel_hi:[1,0]
	v_pk_add_f32 v[52:53], v[136:137], 1.0 op_sel_hi:[1,0]
	global_load_dwordx4 v[136:139], v[170:171], off
	v_pk_mul_f32 v[40:41], v[40:41], v[132:133]
	v_pk_mul_f32 v[42:43], v[42:43], v[134:135]
	global_load_dwordx4 v[132:135], v[78:79], off
	s_waitcnt vmcnt(16)
	v_pk_add_f32 v[48:49], v[142:143], 1.0 op_sel_hi:[1,0]
	v_pk_add_f32 v[50:51], v[140:141], 1.0 op_sel_hi:[1,0]
	global_load_dwordx4 v[140:143], v[70:71], off
	s_waitcnt vmcnt(16)
	v_pk_fma_f32 v[46:47], v[46:47], v[54:55], v[146:147]
	v_pk_fma_f32 v[44:45], v[44:45], v[52:53], v[144:145]
	global_load_dwordx4 v[144:147], v[76:77], off offset:1024
	s_waitcnt vmcnt(16)
	v_pk_fma_f32 v[42:43], v[42:43], v[48:49], v[154:155]
	v_pk_fma_f32 v[40:41], v[40:41], v[50:51], v[152:153]
	global_load_dwordx4 v[152:155], v[78:79], off offset:1024
	v_cvt_pk_bf16_f32 v88, v44, v45
	v_cvt_pk_bf16_f32 v89, v46, v47
	v_cvt_pk_bf16_f32 v90, v40, v41
	v_cvt_pk_bf16_f32 v91, v42, v43
	global_store_dwordx2 v[56:57], v[88:89], off offset:1024
	global_store_dwordx2 v[58:59], v[90:91], off offset:1024
	s_mov_b64 s[26:27], 0
	s_waitcnt vmcnt(18)
	v_pk_mul_f32 v[34:35], v[34:35], v[158:159]
	v_pk_mul_f32 v[36:37], v[36:37], v[156:157]
	v_pk_mul_f32 v[38:39], v[38:39], v[158:159]
	s_waitcnt vmcnt(16)
	v_pk_add_f32 v[42:43], v[164:165], 1.0 op_sel_hi:[1,0]
	v_pk_mul_f32 v[32:33], v[32:33], v[156:157]
	global_load_dwordx4 v[156:159], v[168:169], off offset:1024
	s_waitcnt vmcnt(14)
; __device__ __forceinline__ unsigned cvt_pk_bf16(float lo, float hi) { unsigned r; asm volatile("v_cvt_pk_bf16_f32 %0, %1, %2" : "=v"(r) : "v"(lo), "v"(hi)); return r; }
; __device__ __forceinline__ void p1_row2(int rowA, int rowB, const float* __restrict__ xsrc, const float* __restrict__ csrc, const float* __restrict__ modl,
;                                         const float* __restrict__ nw, bf16_t* __restrict__ H, int lane) {
;     ...
; #pragma unroll
;     for (int j = 0; j < 8; ++j) { const f32x4 w4 = nwp[64 * j];
;         const f32x4 ya = va[j] * ra * w4 * (sca[64 * j] + 1.f) + sha[64 * j], yb = vb[j] * rb * w4 * (scb[64 * j] + 1.f) + shb[64 * j];
;         u32x2 wa, wb; wa.x = cvt_pk_bf16(ya[0], ya[1]); wa.y = cvt_pk_bf16(ya[2], ya[3]); wb.x = cvt_pk_bf16(yb[0], yb[1]); wb.y = cvt_pk_bf16(yb[2], yb[3]);
;         oa[64 * j] = wa; ob[64 * j] = wb; }
	v_pk_fma_f32 v[36:37], v[36:37], v[42:43], v[116:117]
	v_pk_add_f32 v[46:47], v[162:163], 1.0 op_sel_hi:[1,0]
	v_pk_add_f32 v[44:45], v[160:161], 1.0 op_sel_hi:[1,0]
	global_load_dwordx4 v[160:163], v[170:171], off offset:1024
	v_pk_add_f32 v[40:41], v[166:167], 1.0 op_sel_hi:[1,0]
	global_load_dwordx4 v[164:167], v[72:73], off
	s_waitcnt vmcnt(15)
	v_pk_fma_f32 v[34:35], v[34:35], v[46:47], v[114:115]
	v_pk_fma_f32 v[32:33], v[32:33], v[44:45], v[112:113]
	global_load_dwordx4 v[112:115], v[76:77], off offset:2048
	v_pk_fma_f32 v[38:39], v[38:39], v[40:41], v[118:119]
	global_load_dwordx4 v[116:119], v[78:79], off offset:2048
	v_cvt_pk_bf16_f32 v52, v32, v33
	v_cvt_pk_bf16_f32 v53, v34, v35
	v_cvt_pk_bf16_f32 v54, v36, v37
	v_cvt_pk_bf16_f32 v55, v38, v39
	global_store_dwordx2 v[56:57], v[52:53], off offset:1536
	global_store_dwordx2 v[58:59], v[54:55], off offset:1536
	s_waitcnt vmcnt(17)
	v_pk_mul_f32 v[28:29], v[28:29], v[120:121]
	v_pk_mul_f32 v[30:31], v[30:31], v[122:123]
	v_pk_add_f32 v[38:39], v[126:127], 1.0 op_sel_hi:[1,0]
	v_pk_add_f32 v[36:37], v[124:125], 1.0 op_sel_hi:[1,0]
	global_load_dwordx4 v[124:127], v[170:171], off offset:2048
	v_pk_mul_f32 v[24:25], v[24:25], v[120:121]
	v_pk_mul_f32 v[26:27], v[26:27], v[122:123]
	global_load_dwordx4 v[120:123], v[168:169], off offset:2048
	s_waitcnt vmcnt(14)
	v_pk_add_f32 v[32:33], v[134:135], 1.0 op_sel_hi:[1,0]
	v_pk_add_f32 v[34:35], v[132:133], 1.0 op_sel_hi:[1,0]
	global_load_dwordx4 v[132:135], v[76:77], off offset:3072
	v_pk_fma_f32 v[30:31], v[30:31], v[38:39], v[130:131]
	v_pk_fma_f32 v[28:29], v[28:29], v[36:37], v[128:129]
	global_load_dwordx4 v[128:131], v[74:75], off
	v_pk_fma_f32 v[26:27], v[26:27], v[32:33], v[138:139]
	v_pk_fma_f32 v[24:25], v[24:25], v[34:35], v[136:137]
	global_load_dwordx4 v[136:139], v[78:79], off offset:3072
	v_cvt_pk_bf16_f32 v44, v28, v29
	v_cvt_pk_bf16_f32 v45, v30, v31
	v_cvt_pk_bf16_f32 v46, v24, v25
	v_cvt_pk_bf16_f32 v47, v26, v27
	global_store_dwordx2 v[56:57], v[44:45], off offset:2048
	global_store_dwordx2 v[58:59], v[46:47], off offset:2048
	s_waitcnt vmcnt(18)
	v_pk_mul_f32 v[20:21], v[20:21], v[140:141]
	v_pk_mul_f32 v[22:23], v[22:23], v[142:143]
	s_waitcnt vmcnt(17)
	v_pk_add_f32 v[30:31], v[146:147], 1.0 op_sel_hi:[1,0]
	v_pk_add_f32 v[28:29], v[144:145], 1.0 op_sel_hi:[1,0]
	global_load_dwordx4 v[144:147], v[170:171], off offset:3072
	v_pk_mul_f32 v[16:17], v[16:17], v[140:141]
	v_pk_mul_f32 v[18:19], v[18:19], v[142:143]
	global_load_dwordx4 v[140:143], v[168:169], off offset:3072
	s_waitcnt vmcnt(18)
	v_pk_add_f32 v[24:25], v[154:155], 1.0 op_sel_hi:[1,0]
	v_pk_add_f32 v[26:27], v[152:153], 1.0 op_sel_hi:[1,0]
	s_waitcnt vmcnt(15)
	v_pk_fma_f32 v[22:23], v[22:23], v[30:31], v[158:159]
	v_pk_fma_f32 v[20:21], v[20:21], v[28:29], v[156:157]
	s_waitcnt vmcnt(14)
	v_pk_fma_f32 v[18:19], v[18:19], v[24:25], v[162:163]
	v_pk_fma_f32 v[16:17], v[16:17], v[26:27], v[160:161]
	v_cvt_pk_bf16_f32 v36, v20, v21
	v_cvt_pk_bf16_f32 v37, v22, v23
	v_cvt_pk_bf16_f32 v38, v16, v17
	v_cvt_pk_bf16_f32 v39, v18, v19
	global_store_dwordx2 v[56:57], v[36:37], off offset:2560
	global_store_dwordx2 v[58:59], v[38:39], off offset:2560
	s_waitcnt vmcnt(15)
	v_pk_mul_f32 v[12:13], v[12:13], v[164:165]
	v_pk_mul_f32 v[14:15], v[14:15], v[166:167]
	s_waitcnt vmcnt(14)
	v_pk_add_f32 v[22:23], v[114:115], 1.0 op_sel_hi:[1,0]
	v_pk_add_f32 v[20:21], v[112:113], 1.0 op_sel_hi:[1,0]
	v_pk_mul_f32 v[8:9], v[8:9], v[164:165]
	v_pk_mul_f32 v[10:11], v[10:11], v[166:167]
	s_waitcnt vmcnt(13)
	v_pk_add_f32 v[16:17], v[118:119], 1.0 op_sel_hi:[1,0]
	v_pk_add_f32 v[18:19], v[116:117], 1.0 op_sel_hi:[1,0]
	s_waitcnt vmcnt(9)
	v_pk_fma_f32 v[14:15], v[14:15], v[22:23], v[122:123]
	v_pk_fma_f32 v[12:13], v[12:13], v[20:21], v[120:121]
	v_pk_fma_f32 v[10:11], v[10:11], v[16:17], v[126:127]
	v_pk_fma_f32 v[8:9], v[8:9], v[18:19], v[124:125]
	v_cvt_pk_bf16_f32 v28, v12, v13
	v_cvt_pk_bf16_f32 v29, v14, v15
	v_cvt_pk_bf16_f32 v30, v8, v9
	v_cvt_pk_bf16_f32 v31, v10, v11
	global_store_dwordx2 v[56:57], v[28:29], off offset:3072
	global_store_dwordx2 v[58:59], v[30:31], off offset:3072
	s_waitcnt vmcnt(9)
	v_pk_mul_f32 v[4:5], v[4:5], v[128:129]
	v_pk_mul_f32 v[6:7], v[6:7], v[130:131]
	v_pk_add_f32 v[12:13], v[132:133], 1.0 op_sel_hi:[1,0]
	v_pk_mul_f32 v[0:1], v[0:1], v[128:129]
	v_pk_mul_f32 v[2:3], v[2:3], v[130:131]
	s_waitcnt vmcnt(8)
	v_pk_add_f32 v[10:11], v[136:137], 1.0 op_sel_hi:[1,0]
	v_pk_add_f32 v[14:15], v[134:135], 1.0 op_sel_hi:[1,0]
	v_pk_add_f32 v[8:9], v[138:139], 1.0 op_sel_hi:[1,0]
	s_waitcnt vmcnt(4)
	v_pk_fma_f32 v[4:5], v[4:5], v[12:13], v[140:141]
	v_pk_fma_f32 v[0:1], v[0:1], v[10:11], v[144:145]
	v_pk_fma_f32 v[6:7], v[6:7], v[14:15], v[142:143]
	v_pk_fma_f32 v[2:3], v[2:3], v[8:9], v[146:147]
	v_cvt_pk_bf16_f32 v4, v4, v5
	v_cvt_pk_bf16_f32 v5, v6, v7
	v_cvt_pk_bf16_f32 v0, v0, v1
	v_cvt_pk_bf16_f32 v1, v2, v3
	global_store_dwordx2 v[56:57], v[4:5], off offset:3584
